# P0+mlp1: bias loads hoisted to tile top (spare const VGPRs), epilogue vmcnt(0) and tile-top vmcnt(0) removed
# speedup vs baseline: 1.0044x; 1.0028x over previous
; #define GAS __attribute__((address_space(1)))
; __device__ __forceinline__ unsigned cvt_pk_bf16(float lo, float hi) { unsigned r; asm volatile("v_cvt_pk_bf16_f32 %0, %1, %2" : "=v"(r) : "v"(lo), "v"(hi)); return r; }
;     __device__ __forceinline__ void operator()(const f32x4 (&acc)[2][2][4][2], const Unit& u, int wr, int wc, int fr, int fq) const { base(acc, u, wr, wc, fr, fq); }
;     __device__ __forceinline__ void operator()(const f32x4 (&acc)[2][2][4][2], const Unit& u, int wr, int wc, int fr, int fq) const {
;         const int row0 = u.pm * BM + wr * 64 + fr, col0 = u.pn * BM + wc * 32 + 8 * fq;
;         f32x4 bv[2][2];
; #pragma unroll
;         for (int bj = 0; bj < 2; ++bj)
; #pragma unroll
;             for (int n = 0; n < 2; ++n) bv[bj][n] = bias ? *(const GAS f32x4*)(bias + col0 + bj * HALF + 4 * n) : (f32x4){0.f, 0.f, 0.f, 0.f};
; #pragma unroll
;         for (int ai = 0; ai < 2; ++ai)
; #pragma unroll
;             for (int m = 0; m < 4; ++m) { GAS bf16_t* rowp = O + (size_t)(row0 + ai * HALF + m * 16) * ldc + col0;
; #pragma unroll
;                 for (int bj = 0; bj < 2; ++bj) { f32x4 v0 = acc[ai][bj][m][0] + bv[bj][0], v1 = acc[ai][bj][m][1] + bv[bj][1];
;                     if (ACT == 1) {
; #pragma unroll
;                         for (int j = 0; j < 4; ++j) { const float a = fmaxf(v0[j], 0.f), b = fmaxf(v1[j], 0.f); v0[j] = a * a; v1[j] = b * b; } }
;                     u32x4 w; w.x = cvt_pk_bf16(v0[0], v0[1]); w.y = cvt_pk_bf16(v0[2], v0[3]); w.z = cvt_pk_bf16(v1[0], v1[1]); w.w = cvt_pk_bf16(v1[2], v1[3]);
;                     *(GAS u32x4*)(rowp + bj * HALF) = w; } }
.LBB0_459:
	v_lshl_add_u32 v163, s55, 8, v1
	v_mov_b64_e32 v[156:157], s[8:9]
	v_mad_i64_i32 v[164:165], s[34:35], v163, s74, v[156:157]
	v_lshlrev_b64 v[158:159], 1, v[158:159]
	v_lshl_add_u64 v[164:165], v[164:165], 0, v[158:159]
	v_pk_add_f32 v[128:129], v[128:129], v[230:231]
	v_pk_add_f32 v[126:127], v[126:127], v[228:229]
	v_pk_add_f32 v[166:167], v[124:125], v[234:235]
	v_pk_add_f32 v[124:125], v[122:123], v[232:233]
	v_cvt_pk_bf16_f32 v122, v126, v127
	v_cvt_pk_bf16_f32 v123, v128, v129
	v_pk_add_f32 v[118:119], v[118:119], v[236:237]
	v_cvt_pk_bf16_f32 v124, v124, v125
	v_cvt_pk_bf16_f32 v125, v166, v167
	global_store_dwordx4 v[164:165], v[122:125], off
	v_pk_add_f32 v[120:121], v[120:121], v[238:239]
	v_pk_add_f32 v[114:115], v[114:115], v[228:229]
	v_pk_add_f32 v[122:123], v[112:113], v[242:243]
	v_pk_add_f32 v[112:113], v[110:111], v[240:241]
	v_cvt_pk_bf16_f32 v110, v118, v119
	v_cvt_pk_bf16_f32 v111, v120, v121
	v_pk_add_f32 v[102:103], v[102:103], v[236:237]
	v_cvt_pk_bf16_f32 v112, v112, v113
	v_cvt_pk_bf16_f32 v113, v122, v123
	global_store_dwordx4 v[164:165], v[110:113], off offset:256
	v_pk_add_f32 v[104:105], v[104:105], v[238:239]
	v_pk_add_f32 v[98:99], v[98:99], v[228:229]
	v_or_b32_e32 v110, 16, v163
	v_mad_i64_i32 v[110:111], s[34:35], v110, s74, v[156:157]
	v_lshl_add_u64 v[110:111], v[110:111], 0, v[158:159]
	v_pk_add_f32 v[112:113], v[116:117], v[230:231]
	v_pk_add_f32 v[116:117], v[108:109], v[234:235]
	v_pk_add_f32 v[108:109], v[106:107], v[232:233]
	v_cvt_pk_bf16_f32 v106, v114, v115
	v_cvt_pk_bf16_f32 v107, v112, v113
	v_pk_add_f32 v[86:87], v[86:87], v[236:237]
	v_cvt_pk_bf16_f32 v108, v108, v109
	v_cvt_pk_bf16_f32 v109, v116, v117
	global_store_dwordx4 v[110:111], v[106:109], off
	v_pk_add_f32 v[88:89], v[88:89], v[238:239]
	v_pk_add_f32 v[82:83], v[82:83], v[228:229]
	v_pk_add_f32 v[106:107], v[96:97], v[242:243]
	v_pk_add_f32 v[96:97], v[94:95], v[240:241]
	v_cvt_pk_bf16_f32 v94, v102, v103
	v_cvt_pk_bf16_f32 v95, v104, v105
	v_pk_add_f32 v[70:71], v[70:71], v[236:237]
	v_cvt_pk_bf16_f32 v96, v96, v97
	v_cvt_pk_bf16_f32 v97, v106, v107
	global_store_dwordx4 v[110:111], v[94:97], off offset:256
	v_pk_add_f32 v[72:73], v[72:73], v[238:239]
	v_pk_add_f32 v[64:65], v[64:65], v[230:231]
	v_or_b32_e32 v94, 32, v163
	v_mad_i64_i32 v[94:95], s[34:35], v94, s74, v[156:157]
	v_lshl_add_u64 v[94:95], v[94:95], 0, v[158:159]
	v_pk_add_f32 v[96:97], v[100:101], v[230:231]
	v_pk_add_f32 v[100:101], v[92:93], v[234:235]
	v_pk_add_f32 v[92:93], v[90:91], v[232:233]
	v_cvt_pk_bf16_f32 v90, v98, v99
	v_cvt_pk_bf16_f32 v91, v96, v97
	v_pk_add_f32 v[62:63], v[62:63], v[228:229]
	v_cvt_pk_bf16_f32 v92, v92, v93
	v_cvt_pk_bf16_f32 v93, v100, v101
	global_store_dwordx4 v[94:95], v[90:93], off
	v_pk_add_f32 v[54:55], v[54:55], v[236:237]
	v_pk_add_f32 v[56:57], v[56:57], v[238:239]
	v_pk_add_f32 v[90:91], v[80:81], v[242:243]
	v_pk_add_f32 v[80:81], v[78:79], v[240:241]
	v_cvt_pk_bf16_f32 v78, v86, v87
	v_cvt_pk_bf16_f32 v79, v88, v89
	v_pk_add_f32 v[50:51], v[50:51], v[228:229]
	v_cvt_pk_bf16_f32 v80, v80, v81
	v_cvt_pk_bf16_f32 v81, v90, v91
	global_store_dwordx4 v[94:95], v[78:81], off offset:256
	v_pk_add_f32 v[38:39], v[38:39], v[236:237]
	v_pk_add_f32 v[40:41], v[40:41], v[238:239]
	v_or_b32_e32 v78, 48, v163
	v_mad_i64_i32 v[78:79], s[34:35], v78, s74, v[156:157]
	v_lshl_add_u64 v[78:79], v[78:79], 0, v[158:159]
	v_pk_add_f32 v[80:81], v[84:85], v[230:231]
	v_pk_add_f32 v[84:85], v[76:77], v[234:235]
	v_pk_add_f32 v[76:77], v[74:75], v[232:233]
	v_cvt_pk_bf16_f32 v74, v82, v83
	v_cvt_pk_bf16_f32 v75, v80, v81
	v_pk_add_f32 v[34:35], v[34:35], v[228:229]
	v_cvt_pk_bf16_f32 v76, v76, v77
; #define GAS __attribute__((address_space(1)))
; __device__ __forceinline__ unsigned cvt_pk_bf16(float lo, float hi) { unsigned r; asm volatile("v_cvt_pk_bf16_f32 %0, %1, %2" : "=v"(r) : "v"(lo), "v"(hi)); return r; }
;     __device__ __forceinline__ void operator()(const f32x4 (&acc)[2][2][4][2], const Unit& u, int wr, int wc, int fr, int fq) const {
;     ...
;         for (int ai = 0; ai < 2; ++ai)
; #pragma unroll
;             for (int m = 0; m < 4; ++m) { GAS bf16_t* rowp = O + (size_t)(row0 + ai * HALF + m * 16) * ldc + col0;
; #pragma unroll
;                 for (int bj = 0; bj < 2; ++bj) { f32x4 v0 = acc[ai][bj][m][0] + bv[bj][0], v1 = acc[ai][bj][m][1] + bv[bj][1];
;                     if (ACT == 1) {
; #pragma unroll
;                         for (int j = 0; j < 4; ++j) { const float a = fmaxf(v0[j], 0.f), b = fmaxf(v1[j], 0.f); v0[j] = a * a; v1[j] = b * b; } }
;                     u32x4 w; w.x = cvt_pk_bf16(v0[0], v0[1]); w.y = cvt_pk_bf16(v0[2], v0[3]); w.z = cvt_pk_bf16(v1[0], v1[1]); w.w = cvt_pk_bf16(v1[2], v1[3]);
;                     *(GAS u32x4*)(rowp + bj * HALF) = w; } }
	v_cvt_pk_bf16_f32 v77, v84, v85
	global_store_dwordx4 v[78:79], v[74:77], off
	v_pk_add_f32 v[22:23], v[22:23], v[236:237]
	v_pk_add_f32 v[24:25], v[24:25], v[238:239]
	v_pk_add_f32 v[74:75], v[68:69], v[242:243]
	v_pk_add_f32 v[68:69], v[66:67], v[240:241]
	v_cvt_pk_bf16_f32 v66, v70, v71
	v_cvt_pk_bf16_f32 v67, v72, v73
	v_pk_add_f32 v[18:19], v[18:19], v[228:229]
	v_cvt_pk_bf16_f32 v68, v68, v69
	v_cvt_pk_bf16_f32 v69, v74, v75
	global_store_dwordx4 v[78:79], v[66:69], off offset:256
	s_and_b64 vcc, exec, s[38:39]
	s_mov_b32 s56, s18
	v_add_u32_e32 v66, 0x80, v163
	v_mad_i64_i32 v[66:67], s[34:35], v66, s74, v[156:157]
	v_lshl_add_u64 v[66:67], v[66:67], 0, v[158:159]
	v_pk_add_f32 v[68:69], v[60:61], v[234:235]
	v_pk_add_f32 v[60:61], v[58:59], v[232:233]
	v_cvt_pk_bf16_f32 v58, v62, v63
	v_cvt_pk_bf16_f32 v59, v64, v65
	s_mov_b32 s55, s22
	v_cvt_pk_bf16_f32 v60, v60, v61
	v_cvt_pk_bf16_f32 v61, v68, v69
	global_store_dwordx4 v[66:67], v[58:61], off
	s_mov_b64 s[40:41], s[24:25]
	v_pk_add_f32 v[8:9], v[8:9], v[238:239]
	v_pk_add_f32 v[58:59], v[48:49], v[242:243]
	v_pk_add_f32 v[48:49], v[46:47], v[240:241]
	v_cvt_pk_bf16_f32 v46, v54, v55
	v_cvt_pk_bf16_f32 v47, v56, v57
	v_pk_add_f32 v[6:7], v[6:7], v[236:237]
	v_cvt_pk_bf16_f32 v48, v48, v49
	v_cvt_pk_bf16_f32 v49, v58, v59
	global_store_dwordx4 v[66:67], v[46:49], off offset:256
	s_nop 1
	v_add_u32_e32 v46, 0x90, v163
	v_mad_i64_i32 v[46:47], s[34:35], v46, s74, v[156:157]
	v_lshl_add_u64 v[46:47], v[46:47], 0, v[158:159]
	v_pk_add_f32 v[48:49], v[52:53], v[230:231]
	v_pk_add_f32 v[52:53], v[44:45], v[234:235]
	v_pk_add_f32 v[44:45], v[42:43], v[232:233]
	v_cvt_pk_bf16_f32 v42, v50, v51
	v_cvt_pk_bf16_f32 v43, v48, v49
	s_nop 0
	v_cvt_pk_bf16_f32 v44, v44, v45
	v_cvt_pk_bf16_f32 v45, v52, v53
	global_store_dwordx4 v[46:47], v[42:45], off
	s_nop 1
	v_pk_add_f32 v[42:43], v[32:33], v[242:243]
	v_pk_add_f32 v[32:33], v[30:31], v[240:241]
	v_cvt_pk_bf16_f32 v30, v38, v39
	v_cvt_pk_bf16_f32 v31, v40, v41
	s_nop 0
	v_cvt_pk_bf16_f32 v32, v32, v33
	v_cvt_pk_bf16_f32 v33, v42, v43
	global_store_dwordx4 v[46:47], v[30:33], off offset:256
	s_nop 1
	v_add_u32_e32 v30, 0xa0, v163
	v_mad_i64_i32 v[30:31], s[34:35], v30, s74, v[156:157]
	v_lshl_add_u64 v[30:31], v[30:31], 0, v[158:159]
	v_pk_add_f32 v[32:33], v[36:37], v[230:231]
	v_pk_add_f32 v[36:37], v[28:29], v[234:235]
	v_pk_add_f32 v[28:29], v[26:27], v[232:233]
	v_cvt_pk_bf16_f32 v26, v34, v35
	v_cvt_pk_bf16_f32 v27, v32, v33
	s_nop 0
	v_cvt_pk_bf16_f32 v28, v28, v29
	v_cvt_pk_bf16_f32 v29, v36, v37
	global_store_dwordx4 v[30:31], v[26:29], off
	s_nop 1
	v_pk_add_f32 v[26:27], v[16:17], v[242:243]
	v_pk_add_f32 v[16:17], v[14:15], v[240:241]
	v_cvt_pk_bf16_f32 v14, v22, v23
	v_cvt_pk_bf16_f32 v15, v24, v25
	s_nop 0
	v_cvt_pk_bf16_f32 v16, v16, v17
	v_cvt_pk_bf16_f32 v17, v26, v27
	global_store_dwordx4 v[30:31], v[14:17], off offset:256
	s_nop 1
	v_add_u32_e32 v14, 0xb0, v163
	v_mad_i64_i32 v[14:15], s[34:35], v14, s74, v[156:157]
	v_lshl_add_u64 v[14:15], v[14:15], 0, v[158:159]
	v_pk_add_f32 v[16:17], v[20:21], v[230:231]
	v_pk_add_f32 v[20:21], v[12:13], v[234:235]
	v_pk_add_f32 v[12:13], v[10:11], v[232:233]
	v_cvt_pk_bf16_f32 v10, v18, v19
	v_cvt_pk_bf16_f32 v11, v16, v17
	s_mov_b64 s[34:35], s[26:27]
	v_cvt_pk_bf16_f32 v12, v12, v13
	v_cvt_pk_bf16_f32 v13, v20, v21
	global_store_dwordx4 v[14:15], v[10:13], off
	s_nop 1
	v_pk_add_f32 v[10:11], v[4:5], v[242:243]
	v_pk_add_f32 v[4:5], v[2:3], v[240:241]
	v_cvt_pk_bf16_f32 v2, v6, v7
	v_cvt_pk_bf16_f32 v3, v8, v9
	s_nop 0
	v_cvt_pk_bf16_f32 v4, v4, v5
	v_cvt_pk_bf16_f32 v5, v10, v11
	global_store_dwordx4 v[14:15], v[2:5], off offset:256
	s_cbranch_vccnz .LBB0_472

; #define GAS __attribute__((address_space(1)))
; template <class Epi, class Sched, bool ALIGN_EPI, bool SP2>
; __device__ __forceinline__ void gemm_phase(LAS unsigned char* lds, const int tid, const Gemm g, const Sched& S, const Epi& E) {
;     ...
;         bool rst = true; if constexpr (Epi::KEEPS) rst = E.reset(cur);
;         if (rst) {
; #pragma unroll
;         for (int a = 0; a < 2; ++a)
; #pragma unroll
;             for (int b = 0; b < 2; ++b)
; #pragma unroll
;                 for (int m = 0; m < 4; ++m)
; #pragma unroll
;                     for (int n = 0; n < 2; ++n) acc[a][b][m][n] = (f32x4){0.f, 0.f, 0.f, 0.f};
;         }
;         cur = nxt; cA = nA; cB = nB; ++ui;
;     __device__ __forceinline__ void operator()(const f32x4 (&acc)[2][2][4][2], const Unit& u, int wr, int wc, int fr, int fq) const {
;     ...
;         for (int bj = 0; bj < 2; ++bj)
; #pragma unroll
;             for (int n = 0; n < 2; ++n) bv[bj][n] = bias ? *(const GAS f32x4*)(bias + col0 + bj * HALF + 4 * n) : (f32x4){0.f, 0.f, 0.f, 0.f};
.LBB0_462:
	v_mov_b64_e32 v[2:3], 0x6c0
	s_ashr_i32 s23, s22, 31
	v_cmp_lt_i64_e32 vcc, s[24:25], v[2:3]
	s_lshl_b64 s[24:25], s[22:23], 20
	s_add_u32 s24, s5, s24
	s_addc_u32 s25, s44, s25
	s_and_b64 s[26:27], vcc, exec
	s_cselect_b32 s23, s25, s41
	s_cselect_b32 s58, s24, s40
	s_ashr_i32 s19, s18, 31
	s_lshl_b64 s[26:27], s[18:19], 20
	s_add_u32 s26, s45, s26
	s_addc_u32 s27, s46, s27
	s_and_b64 s[42:43], vcc, exec
	s_cselect_b32 s19, s27, s35
	s_cselect_b32 s59, s26, s34
	s_add_u32 s60, s34, 0x100
	s_addc_u32 s61, s35, 0
	s_add_u32 s34, s40, 0x80080
	v_lshl_or_b32 v158, s56, 8, v161
	v_ashrrev_i32_e32 v159, 31, v158
	v_lshl_add_u64 v[156:157], v[158:159], 2, s[10:11]
	global_load_dwordx4 v[228:231], v[156:157], off
	global_load_dwordx4 v[232:235], v[156:157], off offset:16
	global_load_dwordx4 v[236:239], v[156:157], off offset:512
	global_load_dwordx4 v[240:243], v[156:157], off offset:528
	v_mov_b32_e32 v2, 0
	s_addc_u32 s35, s41, 0
	s_mov_b32 s62, -2
	v_mov_b32_e32 v3, v2
	v_mov_b32_e32 v4, v2
	v_mov_b32_e32 v5, v2
	v_mov_b32_e32 v6, v2
	v_mov_b32_e32 v7, v2
	v_mov_b32_e32 v8, v2
	v_mov_b32_e32 v9, v2
	v_mov_b32_e32 v14, v2
	v_mov_b32_e32 v15, v2
	v_mov_b32_e32 v16, v2
	v_mov_b32_e32 v17, v2
	v_mov_b32_e32 v22, v2
	v_mov_b32_e32 v23, v2
	v_mov_b32_e32 v24, v2
	v_mov_b32_e32 v25, v2
	v_mov_b32_e32 v30, v2
	v_mov_b32_e32 v31, v2
	v_mov_b32_e32 v32, v2
	v_mov_b32_e32 v33, v2
	v_mov_b32_e32 v38, v2
	v_mov_b32_e32 v39, v2
	v_mov_b32_e32 v40, v2
	v_mov_b32_e32 v41, v2
	v_mov_b32_e32 v46, v2
	v_mov_b32_e32 v47, v2
	v_mov_b32_e32 v48, v2
	v_mov_b32_e32 v49, v2
	v_mov_b32_e32 v54, v2
	v_mov_b32_e32 v55, v2
	v_mov_b32_e32 v56, v2
	v_mov_b32_e32 v57, v2
	v_mov_b32_e32 v10, v2
	v_mov_b32_e32 v11, v2
	v_mov_b32_e32 v12, v2
	v_mov_b32_e32 v13, v2
	v_mov_b32_e32 v18, v2
	v_mov_b32_e32 v19, v2
	v_mov_b32_e32 v20, v2
	v_mov_b32_e32 v21, v2
	v_mov_b32_e32 v26, v2
	v_mov_b32_e32 v27, v2
	v_mov_b32_e32 v28, v2
	v_mov_b32_e32 v29, v2
	v_mov_b32_e32 v34, v2
	v_mov_b32_e32 v35, v2
	v_mov_b32_e32 v36, v2
	v_mov_b32_e32 v37, v2
	v_mov_b32_e32 v42, v2
	v_mov_b32_e32 v43, v2
	v_mov_b32_e32 v44, v2
	v_mov_b32_e32 v45, v2
	v_mov_b32_e32 v50, v2
	v_mov_b32_e32 v51, v2
	v_mov_b32_e32 v52, v2
	v_mov_b32_e32 v53, v2
	v_mov_b32_e32 v58, v2
	v_mov_b32_e32 v59, v2
	v_mov_b32_e32 v60, v2
	v_mov_b32_e32 v61, v2
	v_mov_b32_e32 v62, v2
	v_mov_b32_e32 v63, v2
	v_mov_b32_e32 v64, v2
	v_mov_b32_e32 v65, v2
	v_mov_b32_e32 v66, v2
	v_mov_b32_e32 v67, v2
	v_mov_b32_e32 v68, v2
	v_mov_b32_e32 v69, v2
	v_mov_b32_e32 v70, v2
	v_mov_b32_e32 v71, v2
	v_mov_b32_e32 v72, v2
	v_mov_b32_e32 v73, v2
	v_mov_b32_e32 v78, v2
	v_mov_b32_e32 v79, v2
	v_mov_b32_e32 v80, v2
	v_mov_b32_e32 v81, v2
	v_mov_b32_e32 v86, v2
	v_mov_b32_e32 v87, v2
	v_mov_b32_e32 v88, v2
	v_mov_b32_e32 v89, v2
	v_mov_b32_e32 v94, v2
	v_mov_b32_e32 v95, v2
	v_mov_b32_e32 v96, v2
	v_mov_b32_e32 v97, v2
	v_mov_b32_e32 v102, v2
	v_mov_b32_e32 v103, v2
	v_mov_b32_e32 v104, v2
	v_mov_b32_e32 v105, v2
	v_mov_b32_e32 v110, v2
	v_mov_b32_e32 v111, v2
	v_mov_b32_e32 v112, v2
	v_mov_b32_e32 v113, v2
	v_mov_b32_e32 v118, v2
	v_mov_b32_e32 v119, v2
	v_mov_b32_e32 v120, v2
	v_mov_b32_e32 v121, v2
	v_mov_b32_e32 v74, v2
	v_mov_b32_e32 v75, v2
	v_mov_b32_e32 v76, v2
	v_mov_b32_e32 v77, v2
	v_mov_b32_e32 v82, v2
	v_mov_b32_e32 v83, v2
	v_mov_b32_e32 v84, v2
	v_mov_b32_e32 v85, v2
	v_mov_b32_e32 v90, v2
	v_mov_b32_e32 v91, v2
	v_mov_b32_e32 v92, v2
	v_mov_b32_e32 v93, v2
	v_mov_b32_e32 v98, v2
	v_mov_b32_e32 v99, v2
	v_mov_b32_e32 v100, v2
	v_mov_b32_e32 v101, v2
	v_mov_b32_e32 v106, v2
	v_mov_b32_e32 v107, v2
	v_mov_b32_e32 v108, v2
	v_mov_b32_e32 v109, v2
	v_mov_b32_e32 v114, v2
	v_mov_b32_e32 v115, v2
	v_mov_b32_e32 v116, v2
	v_mov_b32_e32 v117, v2
	v_mov_b32_e32 v122, v2
	v_mov_b32_e32 v123, v2
	v_mov_b32_e32 v124, v2
	v_mov_b32_e32 v125, v2
	v_mov_b32_e32 v126, v2
	v_mov_b32_e32 v127, v2
	v_mov_b32_e32 v128, v2
	v_mov_b32_e32 v129, v2
.LBB0_463:
	s_add_u32 s40, s34, 0xfff80080
	s_addc_u32 s41, s35, -1
	s_add_i32 s63, 0, 0x10000
	s_cmp_eq_u32 s62, 28
	s_cselect_b32 s43, s23, s41
	s_cselect_b32 s42, s58, s40
	s_cselect_b32 s41, s19, s61
	s_cselect_b32 s40, s59, s60
	s_add_i32 s68, 0, 0x14000
	v_add_u32_e32 v142, s63, v160
	v_add_u32_e32 v163, s68, v160
	ds_read_b128 v[130:133], v142
	ds_read_b128 v[134:137], v142 offset:1024
	ds_read_b128 v[138:141], v142 offset:2048
	ds_read_b128 v[142:145], v142 offset:3072
	ds_read_b128 v[156:159], v163
	ds_read_b128 v[164:167], v163 offset:1024
	ds_read_b128 v[168:171], v163 offset:2048
	ds_read_b128 v[172:175], v163 offset:3072
	v_lshl_add_u64 v[200:201], s[34:35], 0, v[154:155]
	s_add_i32 m0, s48, 0xc000
	ds_read_b128 v[176:179], v162
	ds_read_b128 v[180:183], v162 offset:1024
	ds_read_b128 v[184:187], v162 offset:2048
	ds_read_b128 v[188:191], v162 offset:3072
	ds_read_b128 v[192:195], v162 offset:4096
	ds_read_b128 v[196:199], v162 offset:5120
	ds_read_b128 v[214:217], v162 offset:6144
	ds_read_b128 v[218:221], v162 offset:7168
	global_load_lds_dwordx4 v[200:201], off
	v_lshl_add_u64 v[200:201], s[34:35], 0, v[152:153]
	s_add_i32 m0, s48, 0xe000
	s_nop 0
	global_load_lds_dwordx4 v[200:201], off
	s_waitcnt vmcnt(8)
	s_waitcnt lgkmcnt(0)
	s_barrier
; #define PG8_STAGE(bufoff, gbase, voff) do { _Pragma("unroll") for (int _i = 0; _i < 2; ++_i) \
;         __builtin_amdgcn_global_load_lds((const GAS unsigned*)((const GAS char*)(gbase) + (voff)[_i]), (LAS unsigned*)(lds + (bufoff) + ldsw + _i * 8192), 16, 0, 0); } while (0)
; #define PG8_LDA(dst, b, h) do { _Pragma("unroll") for (int m = 0; m < 4; ++m) _Pragma("unroll") for (int k = 0; k < 2; ++k) dst[m][k] = *(const LAS bf16x8*)(lds + PG8_SA(b, h) + aoff + m * 2048 + k * 1024); } while (0)
; #define PG8_LDB(dst, b, h) do { _Pragma("unroll") for (int n = 0; n < 2; ++n) _Pragma("unroll") for (int k = 0; k < 2; ++k) dst[n][k] = *(const LAS bf16x8*)(lds + PG8_SB(b, h) + boff + n * 2048 + k * 1024); } while (0)
; #define PG8_MMA(ai, bj, At, Bt) do { __builtin_amdgcn_sched_barrier(0); _Pragma("unroll") for (int m = 0; m < 4; ++m) _Pragma("unroll") for (int n = 0; n < 2; ++n) _Pragma("unroll") for (int k = 0; k < 2; ++k) \
;         acc[ai][bj][m][n] = __builtin_amdgcn_mfma_f32_16x16x32_bf16(Bt[n][k], At[m][k], acc[ai][bj][m][n], 0, 0, 0); __builtin_amdgcn_sched_barrier(0); } while (0)
; #define PG8_WAIT_V(n) asm volatile("s_waitcnt vmcnt(" #n ")" ::: "memory")
; #define PG8_WAIT_L(n) asm volatile("s_waitcnt lgkmcnt(" #n ")" ::: "memory")
; #define PG8_BAR __builtin_amdgcn_s_barrier()
; #define PG8_SCHED __builtin_amdgcn_sched_barrier(0)
; template <class Epi, class Sched, bool ALIGN_EPI, bool SP2>
; __device__ __forceinline__ void gemm_phase(LAS unsigned char* lds, const int tid, const Gemm g, const Sched& S, const Epi& E) {
;     ...
;             PG8_LDB(B0, 0, 0); PG8_LDB(B1, 0, 1); PG8_SCHED; PG8_LDA(At, 0, 0); PG8_STAGE(PG8_SA(1, 1), a1 + hstepA, voffA);
;             PG8_WAIT_V(8); PG8_WAIT_L(0); PG8_BAR; PG8_MMA(0, 0, At, B0); PG8_MMA(0, 1, At, B1); PG8_BAR; PG8_SCHED;
;             PG8_LDA(At, 0, 1); PG8_STAGE(PG8_SB(0, 0), b2, voffB); PG8_STAGE(PG8_SB(0, 1), b2 + hstepB, voffB); PG8_STAGE(PG8_SA(0, 0), a2, voffA);
;             PG8_WAIT_V(8); PG8_WAIT_L(0); PG8_BAR; PG8_MMA(1, 0, At, B0); PG8_MMA(1, 1, At, B1); PG8_BAR; PG8_SCHED;
;             PG8_LDB(B0, 1, 0); PG8_LDB(B1, 1, 1); PG8_SCHED; PG8_LDA(At, 1, 0); PG8_STAGE(PG8_SA(0, 1), a2 + hstepA, voffA);
;             PG8_WAIT_V(8); PG8_WAIT_L(0); PG8_BAR; PG8_MMA(0, 0, At, B0); PG8_MMA(0, 1, At, B1); PG8_BAR; PG8_SCHED;
	s_waitcnt lgkmcnt(0)
	v_mfma_f32_16x16x32_bf16 v[126:129], v[130:133], v[176:179], v[126:129]
	v_mfma_f32_16x16x32_bf16 v[122:125], v[138:141], v[176:179], v[122:125]
	v_mfma_f32_16x16x32_bf16 v[114:117], v[130:133], v[184:187], v[114:117]
	v_mfma_f32_16x16x32_bf16 v[106:109], v[138:141], v[184:187], v[106:109]
	v_mfma_f32_16x16x32_bf16 v[98:101], v[130:133], v[192:195], v[98:101]
	v_mfma_f32_16x16x32_bf16 v[90:93], v[138:141], v[192:195], v[90:93]
	v_mfma_f32_16x16x32_bf16 v[82:85], v[130:133], v[214:217], v[82:85]
	v_mfma_f32_16x16x32_bf16 v[74:77], v[138:141], v[214:217], v[74:77]
	v_mfma_f32_16x16x32_bf16 v[126:129], v[134:137], v[180:183], v[126:129]
	v_mfma_f32_16x16x32_bf16 v[122:125], v[142:145], v[180:183], v[122:125]
	v_mfma_f32_16x16x32_bf16 v[114:117], v[134:137], v[188:191], v[114:117]
	v_mfma_f32_16x16x32_bf16 v[106:109], v[142:145], v[188:191], v[106:109]
	v_mfma_f32_16x16x32_bf16 v[98:101], v[134:137], v[196:199], v[98:101]
	v_mfma_f32_16x16x32_bf16 v[90:93], v[142:145], v[196:199], v[90:93]
	v_mfma_f32_16x16x32_bf16 v[82:85], v[134:137], v[218:221], v[82:85]
	v_mfma_f32_16x16x32_bf16 v[74:77], v[142:145], v[218:221], v[74:77]
	v_mfma_f32_16x16x32_bf16 v[118:121], v[156:159], v[176:179], v[118:121]
	v_mfma_f32_16x16x32_bf16 v[110:113], v[168:171], v[176:179], v[110:113]
	v_mfma_f32_16x16x32_bf16 v[102:105], v[156:159], v[184:187], v[102:105]
	v_mfma_f32_16x16x32_bf16 v[94:97], v[168:171], v[184:187], v[94:97]
	v_mfma_f32_16x16x32_bf16 v[86:89], v[156:159], v[192:195], v[86:89]
	v_mfma_f32_16x16x32_bf16 v[78:81], v[168:171], v[192:195], v[78:81]
	v_mfma_f32_16x16x32_bf16 v[70:73], v[156:159], v[214:217], v[70:73]
	v_mfma_f32_16x16x32_bf16 v[66:69], v[168:171], v[214:217], v[66:69]
	v_mfma_f32_16x16x32_bf16 v[118:121], v[164:167], v[180:183], v[118:121]
	v_mfma_f32_16x16x32_bf16 v[110:113], v[172:175], v[180:183], v[110:113]
	v_mfma_f32_16x16x32_bf16 v[102:105], v[164:167], v[188:191], v[102:105]
	v_mfma_f32_16x16x32_bf16 v[94:97], v[172:175], v[188:191], v[94:97]
	v_mfma_f32_16x16x32_bf16 v[86:89], v[164:167], v[196:199], v[86:89]
	v_mfma_f32_16x16x32_bf16 v[78:81], v[172:175], v[196:199], v[78:81]
	v_mfma_f32_16x16x32_bf16 v[70:73], v[164:167], v[218:221], v[70:73]
	v_mfma_f32_16x16x32_bf16 v[66:69], v[172:175], v[218:221], v[66:69]
	s_barrier
	s_add_i32 s63, s63, s47
	v_lshl_add_u64 v[200:201], s[40:41], 0, v[202:203]
	s_mov_b32 m0, s63
	ds_read_b128 v[176:179], v162 offset:16384
	ds_read_b128 v[180:183], v162 offset:17408
	ds_read_b128 v[184:187], v162 offset:18432
	ds_read_b128 v[188:191], v162 offset:19456
	ds_read_b128 v[192:195], v162 offset:20480
	ds_read_b128 v[196:199], v162 offset:21504
	ds_read_b128 v[214:217], v162 offset:22528
	ds_read_b128 v[218:221], v162 offset:23552
	global_load_lds_dwordx4 v[200:201], off
	s_add_i32 m0, s63, 0x2000
	s_add_u32 s64, s40, 0x80000
	v_lshl_add_u64 v[222:223], s[40:41], 0, v[150:151]
	s_addc_u32 s65, s41, 0
	s_add_i32 s63, s68, s47
	global_load_lds_dwordx4 v[222:223], off
	v_lshl_add_u64 v[224:225], s[64:65], 0, v[202:203]
	s_mov_b32 m0, s63
	v_lshl_add_u64 v[226:227], s[42:43], 0, v[148:149]
	global_load_lds_dwordx4 v[224:225], off
	v_lshl_add_u64 v[224:225], s[64:65], 0, v[150:151]
	s_add_i32 m0, s63, 0x2000
	s_nop 0
	global_load_lds_dwordx4 v[224:225], off
	v_lshl_add_u64 v[224:225], s[42:43], 0, v[146:147]
	s_mov_b32 m0, s48
	s_nop 0
	global_load_lds_dwordx4 v[224:225], off
	s_mov_b32 m0, s49
	s_nop 0
	global_load_lds_dwordx4 v[226:227], off
	s_waitcnt vmcnt(8)
	s_waitcnt lgkmcnt(0)
	s_barrier
	s_waitcnt lgkmcnt(0)
	v_mfma_f32_16x16x32_bf16 v[62:65], v[130:133], v[176:179], v[62:65]
	v_mfma_f32_16x16x32_bf16 v[58:61], v[138:141], v[176:179], v[58:61]
	v_mfma_f32_16x16x32_bf16 v[50:53], v[130:133], v[184:187], v[50:53]
	v_mfma_f32_16x16x32_bf16 v[42:45], v[138:141], v[184:187], v[42:45]
	v_mfma_f32_16x16x32_bf16 v[34:37], v[130:133], v[192:195], v[34:37]
	v_mfma_f32_16x16x32_bf16 v[26:29], v[138:141], v[192:195], v[26:29]
	v_mfma_f32_16x16x32_bf16 v[18:21], v[130:133], v[214:217], v[18:21]
	v_mfma_f32_16x16x32_bf16 v[10:13], v[138:141], v[214:217], v[10:13]
	v_mfma_f32_16x16x32_bf16 v[62:65], v[134:137], v[180:183], v[62:65]
	v_mfma_f32_16x16x32_bf16 v[58:61], v[142:145], v[180:183], v[58:61]
	v_mfma_f32_16x16x32_bf16 v[50:53], v[134:137], v[188:191], v[50:53]
	v_mfma_f32_16x16x32_bf16 v[42:45], v[142:145], v[188:191], v[42:45]
	v_mfma_f32_16x16x32_bf16 v[34:37], v[134:137], v[196:199], v[34:37]
	v_mfma_f32_16x16x32_bf16 v[26:29], v[142:145], v[196:199], v[26:29]
	v_mfma_f32_16x16x32_bf16 v[18:21], v[134:137], v[218:221], v[18:21]
	v_mfma_f32_16x16x32_bf16 v[10:13], v[142:145], v[218:221], v[10:13]
	v_mfma_f32_16x16x32_bf16 v[54:57], v[156:159], v[176:179], v[54:57]
	v_mfma_f32_16x16x32_bf16 v[46:49], v[168:171], v[176:179], v[46:49]
	v_mfma_f32_16x16x32_bf16 v[38:41], v[156:159], v[184:187], v[38:41]
	v_mfma_f32_16x16x32_bf16 v[30:33], v[168:171], v[184:187], v[30:33]
	v_mfma_f32_16x16x32_bf16 v[22:25], v[156:159], v[192:195], v[22:25]
	v_mfma_f32_16x16x32_bf16 v[14:17], v[168:171], v[192:195], v[14:17]
	v_mfma_f32_16x16x32_bf16 v[6:9], v[156:159], v[214:217], v[6:9]
	v_mfma_f32_16x16x32_bf16 v[2:5], v[168:171], v[214:217], v[2:5]
	v_mfma_f32_16x16x32_bf16 v[54:57], v[164:167], v[180:183], v[54:57]
	v_mfma_f32_16x16x32_bf16 v[46:49], v[172:175], v[180:183], v[46:49]
	v_mfma_f32_16x16x32_bf16 v[38:41], v[164:167], v[188:191], v[38:41]
	v_mfma_f32_16x16x32_bf16 v[30:33], v[172:175], v[188:191], v[30:33]
	v_mfma_f32_16x16x32_bf16 v[22:25], v[164:167], v[196:199], v[22:25]
	v_mfma_f32_16x16x32_bf16 v[14:17], v[172:175], v[196:199], v[14:17]
	v_mfma_f32_16x16x32_bf16 v[6:9], v[164:167], v[218:221], v[6:9]
	v_mfma_f32_16x16x32_bf16 v[2:5], v[172:175], v[218:221], v[2:5]
	s_barrier
; #define PG8_STAGE(bufoff, gbase, voff) do { _Pragma("unroll") for (int _i = 0; _i < 2; ++_i) \
;         __builtin_amdgcn_global_load_lds((const GAS unsigned*)((const GAS char*)(gbase) + (voff)[_i]), (LAS unsigned*)(lds + (bufoff) + ldsw + _i * 8192), 16, 0, 0); } while (0)
; #define PG8_LDA(dst, b, h) do { _Pragma("unroll") for (int m = 0; m < 4; ++m) _Pragma("unroll") for (int k = 0; k < 2; ++k) dst[m][k] = *(const LAS bf16x8*)(lds + PG8_SA(b, h) + aoff + m * 2048 + k * 1024); } while (0)
; #define PG8_LDB(dst, b, h) do { _Pragma("unroll") for (int n = 0; n < 2; ++n) _Pragma("unroll") for (int k = 0; k < 2; ++k) dst[n][k] = *(const LAS bf16x8*)(lds + PG8_SB(b, h) + boff + n * 2048 + k * 1024); } while (0)
; #define PG8_MMA(ai, bj, At, Bt) do { __builtin_amdgcn_sched_barrier(0); _Pragma("unroll") for (int m = 0; m < 4; ++m) _Pragma("unroll") for (int n = 0; n < 2; ++n) _Pragma("unroll") for (int k = 0; k < 2; ++k) \
;         acc[ai][bj][m][n] = __builtin_amdgcn_mfma_f32_16x16x32_bf16(Bt[n][k], At[m][k], acc[ai][bj][m][n], 0, 0, 0); __builtin_amdgcn_sched_barrier(0); } while (0)
; #define PG8_WAIT_V(n) asm volatile("s_waitcnt vmcnt(" #n ")" ::: "memory")
; #define PG8_WAIT_L(n) asm volatile("s_waitcnt lgkmcnt(" #n ")" ::: "memory")
; #define PG8_BAR __builtin_amdgcn_s_barrier()
; #define PG8_SCHED __builtin_amdgcn_sched_barrier(0)
; template <class Epi, class Sched, bool ALIGN_EPI, bool SP2>
; __device__ __forceinline__ void gemm_phase(LAS unsigned char* lds, const int tid, const Gemm g, const Sched& S, const Epi& E) {
;     ...
;             PG8_LDB(B0, 1, 0); PG8_LDB(B1, 1, 1); PG8_SCHED; PG8_LDA(At, 1, 0); PG8_STAGE(PG8_SA(0, 1), a2 + hstepA, voffA);
;             PG8_WAIT_V(8); PG8_WAIT_L(0); PG8_BAR; PG8_MMA(0, 0, At, B0); PG8_MMA(0, 1, At, B1); PG8_BAR; PG8_SCHED;
	s_add_i32 s63, 0, 0x18000
	s_add_i32 s64, 0, 0x1c000
	v_add_u32_e32 v142, s63, v160
	v_add_u32_e32 v163, s64, v160
	ds_read_b128 v[130:133], v142
	ds_read_b128 v[134:137], v142 offset:1024
	ds_read_b128 v[138:141], v142 offset:2048
	ds_read_b128 v[142:145], v142 offset:3072
	ds_read_b128 v[156:159], v163
	ds_read_b128 v[164:167], v163 offset:1024
	ds_read_b128 v[168:171], v163 offset:2048
	ds_read_b128 v[172:175], v163 offset:3072
	s_add_u32 s42, s42, 0x80000
	s_addc_u32 s43, s43, 0
	s_mov_b32 m0, s50
	v_lshl_add_u64 v[246:247], s[42:43], 0, v[146:147]
	ds_read_b128 v[176:179], v162 offset:32768
	ds_read_b128 v[180:183], v162 offset:33792
	ds_read_b128 v[184:187], v162 offset:34816
	ds_read_b128 v[188:191], v162 offset:35840
	ds_read_b128 v[192:195], v162 offset:36864
	ds_read_b128 v[196:199], v162 offset:37888
	ds_read_b128 v[214:217], v162 offset:38912
	ds_read_b128 v[218:221], v162 offset:39936
	global_load_lds_dwordx4 v[246:247], off
	v_lshl_add_u64 v[246:247], s[42:43], 0, v[148:149]
	s_mov_b32 m0, s51
	s_nop 0
	global_load_lds_dwordx4 v[246:247], off
	s_waitcnt vmcnt(8)
	s_waitcnt lgkmcnt(0)
	s_barrier
	s_waitcnt lgkmcnt(0)
	v_mfma_f32_16x16x32_bf16 v[126:129], v[130:133], v[176:179], v[126:129]
	v_mfma_f32_16x16x32_bf16 v[122:125], v[138:141], v[176:179], v[122:125]
	v_mfma_f32_16x16x32_bf16 v[114:117], v[130:133], v[184:187], v[114:117]
	v_mfma_f32_16x16x32_bf16 v[106:109], v[138:141], v[184:187], v[106:109]
	v_mfma_f32_16x16x32_bf16 v[98:101], v[130:133], v[192:195], v[98:101]
	v_mfma_f32_16x16x32_bf16 v[90:93], v[138:141], v[192:195], v[90:93]
	v_mfma_f32_16x16x32_bf16 v[82:85], v[130:133], v[214:217], v[82:85]
	v_mfma_f32_16x16x32_bf16 v[74:77], v[138:141], v[214:217], v[74:77]
	v_mfma_f32_16x16x32_bf16 v[126:129], v[134:137], v[180:183], v[126:129]
	v_mfma_f32_16x16x32_bf16 v[122:125], v[142:145], v[180:183], v[122:125]
	v_mfma_f32_16x16x32_bf16 v[114:117], v[134:137], v[188:191], v[114:117]
	v_mfma_f32_16x16x32_bf16 v[106:109], v[142:145], v[188:191], v[106:109]
	v_mfma_f32_16x16x32_bf16 v[98:101], v[134:137], v[196:199], v[98:101]
	v_mfma_f32_16x16x32_bf16 v[90:93], v[142:145], v[196:199], v[90:93]
	v_mfma_f32_16x16x32_bf16 v[82:85], v[134:137], v[218:221], v[82:85]
	v_mfma_f32_16x16x32_bf16 v[74:77], v[142:145], v[218:221], v[74:77]
	v_mfma_f32_16x16x32_bf16 v[118:121], v[156:159], v[176:179], v[118:121]
	v_mfma_f32_16x16x32_bf16 v[110:113], v[168:171], v[176:179], v[110:113]
	v_mfma_f32_16x16x32_bf16 v[102:105], v[156:159], v[184:187], v[102:105]
	v_mfma_f32_16x16x32_bf16 v[94:97], v[168:171], v[184:187], v[94:97]
	v_mfma_f32_16x16x32_bf16 v[86:89], v[156:159], v[192:195], v[86:89]
	v_mfma_f32_16x16x32_bf16 v[78:81], v[168:171], v[192:195], v[78:81]
	v_mfma_f32_16x16x32_bf16 v[70:73], v[156:159], v[214:217], v[70:73]
	v_mfma_f32_16x16x32_bf16 v[66:69], v[168:171], v[214:217], v[66:69]
	v_mfma_f32_16x16x32_bf16 v[118:121], v[164:167], v[180:183], v[118:121]
	v_mfma_f32_16x16x32_bf16 v[110:113], v[172:175], v[180:183], v[110:113]
	v_mfma_f32_16x16x32_bf16 v[102:105], v[164:167], v[188:191], v[102:105]
	v_mfma_f32_16x16x32_bf16 v[94:97], v[172:175], v[188:191], v[94:97]
	v_mfma_f32_16x16x32_bf16 v[86:89], v[164:167], v[196:199], v[86:89]
	v_mfma_f32_16x16x32_bf16 v[78:81], v[172:175], v[196:199], v[78:81]
	v_mfma_f32_16x16x32_bf16 v[70:73], v[164:167], v[218:221], v[70:73]
	v_mfma_f32_16x16x32_bf16 v[66:69], v[172:175], v[218:221], v[66:69]
	s_barrier
; #define PG8_STAGE(bufoff, gbase, voff) do { _Pragma("unroll") for (int _i = 0; _i < 2; ++_i) \
;         __builtin_amdgcn_global_load_lds((const GAS unsigned*)((const GAS char*)(gbase) + (voff)[_i]), (LAS unsigned*)(lds + (bufoff) + ldsw + _i * 8192), 16, 0, 0); } while (0)
; #define PG8_LDA(dst, b, h) do { _Pragma("unroll") for (int m = 0; m < 4; ++m) _Pragma("unroll") for (int k = 0; k < 2; ++k) dst[m][k] = *(const LAS bf16x8*)(lds + PG8_SA(b, h) + aoff + m * 2048 + k * 1024); } while (0)
; #define PG8_MMA(ai, bj, At, Bt) do { __builtin_amdgcn_sched_barrier(0); _Pragma("unroll") for (int m = 0; m < 4; ++m) _Pragma("unroll") for (int n = 0; n < 2; ++n) _Pragma("unroll") for (int k = 0; k < 2; ++k) \
;         acc[ai][bj][m][n] = __builtin_amdgcn_mfma_f32_16x16x32_bf16(Bt[n][k], At[m][k], acc[ai][bj][m][n], 0, 0, 0); __builtin_amdgcn_sched_barrier(0); } while (0)
; #define PG8_WAIT_V(n) asm volatile("s_waitcnt vmcnt(" #n ")" ::: "memory")
; #define PG8_WAIT_L(n) asm volatile("s_waitcnt lgkmcnt(" #n ")" ::: "memory")
; #define PG8_BAR __builtin_amdgcn_s_barrier()
; #define PG8_SCHED __builtin_amdgcn_sched_barrier(0)
; template <class Epi, class Sched, bool ALIGN_EPI, bool SP2>
; __device__ __forceinline__ void gemm_phase(LAS unsigned char* lds, const int tid, const Gemm g, const Sched& S, const Epi& E) {
;     ...
;             PG8_LDA(At, 1, 1); PG8_STAGE(PG8_SB(1, 0), b3, voffB); PG8_STAGE(PG8_SB(1, 1), b3 + hstepB, voffB); PG8_STAGE(PG8_SA(1, 0), a3, voffA);
;             PG8_WAIT_V(8); PG8_WAIT_L(0); PG8_BAR; PG8_MMA(1, 0, At, B0); PG8_MMA(1, 1, At, B1); PG8_BAR; PG8_SCHED;
;     ...
;     PG8_WAIT_V(0);
;     if constexpr (!ALIGN_EPI) { if (wr == 0) PG8_BAR; }
;     PG8_BAR;
;     __builtin_amdgcn_s_setprio(0);
	s_add_i32 s42, s63, s47
	v_lshl_add_u64 v[200:201], v[200:201], 0, s[14:15]
	s_mov_b32 m0, s42
	ds_read_b128 v[176:179], v162 offset:49152
	ds_read_b128 v[180:183], v162 offset:50176
	ds_read_b128 v[184:187], v162 offset:51200
	ds_read_b128 v[188:191], v162 offset:52224
	ds_read_b128 v[192:195], v162 offset:53248
	ds_read_b128 v[196:199], v162 offset:54272
	ds_read_b128 v[214:217], v162 offset:55296
	ds_read_b128 v[218:221], v162 offset:56320
	global_load_lds_dwordx4 v[200:201], off
	s_add_i32 m0, s42, 0x2000
	s_add_u32 s40, s40, 0x80080
	v_lshl_add_u64 v[200:201], v[222:223], 0, s[14:15]
	s_addc_u32 s41, s41, 0
	s_add_i32 s42, s64, s47
	global_load_lds_dwordx4 v[200:201], off
	v_lshl_add_u64 v[200:201], s[40:41], 0, v[202:203]
	s_mov_b32 m0, s42
	s_nop 0
	global_load_lds_dwordx4 v[200:201], off
	v_lshl_add_u64 v[200:201], s[40:41], 0, v[150:151]
	s_add_i32 m0, s42, 0x2000
	s_nop 0
	global_load_lds_dwordx4 v[200:201], off
	v_lshl_add_u64 v[200:201], v[224:225], 0, s[14:15]
	s_mov_b32 m0, s52
	s_nop 0
	global_load_lds_dwordx4 v[200:201], off
	v_lshl_add_u64 v[200:201], v[226:227], 0, s[14:15]
	s_mov_b32 m0, s53
	s_nop 0
	global_load_lds_dwordx4 v[200:201], off
	s_waitcnt vmcnt(8)
	s_waitcnt lgkmcnt(0)
	s_barrier
	s_waitcnt lgkmcnt(0)
	v_mfma_f32_16x16x32_bf16 v[62:65], v[130:133], v[176:179], v[62:65]
	v_mfma_f32_16x16x32_bf16 v[58:61], v[138:141], v[176:179], v[58:61]
	v_mfma_f32_16x16x32_bf16 v[50:53], v[130:133], v[184:187], v[50:53]
	v_mfma_f32_16x16x32_bf16 v[42:45], v[138:141], v[184:187], v[42:45]
	v_mfma_f32_16x16x32_bf16 v[34:37], v[130:133], v[192:195], v[34:37]
	v_mfma_f32_16x16x32_bf16 v[26:29], v[138:141], v[192:195], v[26:29]
	v_mfma_f32_16x16x32_bf16 v[18:21], v[130:133], v[214:217], v[18:21]
	v_mfma_f32_16x16x32_bf16 v[10:13], v[138:141], v[214:217], v[10:13]
	v_mfma_f32_16x16x32_bf16 v[62:65], v[134:137], v[180:183], v[62:65]
	v_mfma_f32_16x16x32_bf16 v[58:61], v[142:145], v[180:183], v[58:61]
	v_mfma_f32_16x16x32_bf16 v[50:53], v[134:137], v[188:191], v[50:53]
	v_mfma_f32_16x16x32_bf16 v[42:45], v[142:145], v[188:191], v[42:45]
	v_mfma_f32_16x16x32_bf16 v[34:37], v[134:137], v[196:199], v[34:37]
	v_mfma_f32_16x16x32_bf16 v[26:29], v[142:145], v[196:199], v[26:29]
	v_mfma_f32_16x16x32_bf16 v[18:21], v[134:137], v[218:221], v[18:21]
	v_mfma_f32_16x16x32_bf16 v[10:13], v[142:145], v[218:221], v[10:13]
	v_mfma_f32_16x16x32_bf16 v[54:57], v[156:159], v[176:179], v[54:57]
	v_mfma_f32_16x16x32_bf16 v[46:49], v[168:171], v[176:179], v[46:49]
	v_mfma_f32_16x16x32_bf16 v[38:41], v[156:159], v[184:187], v[38:41]
	v_mfma_f32_16x16x32_bf16 v[30:33], v[168:171], v[184:187], v[30:33]
	v_mfma_f32_16x16x32_bf16 v[22:25], v[156:159], v[192:195], v[22:25]
	v_mfma_f32_16x16x32_bf16 v[14:17], v[168:171], v[192:195], v[14:17]
	v_mfma_f32_16x16x32_bf16 v[6:9], v[156:159], v[214:217], v[6:9]
	v_mfma_f32_16x16x32_bf16 v[2:5], v[168:171], v[214:217], v[2:5]
	v_mfma_f32_16x16x32_bf16 v[54:57], v[164:167], v[180:183], v[54:57]
	v_mfma_f32_16x16x32_bf16 v[46:49], v[172:175], v[180:183], v[46:49]
	v_mfma_f32_16x16x32_bf16 v[38:41], v[164:167], v[188:191], v[38:41]
	v_mfma_f32_16x16x32_bf16 v[30:33], v[172:175], v[188:191], v[30:33]
	v_mfma_f32_16x16x32_bf16 v[22:25], v[164:167], v[196:199], v[22:25]
	v_mfma_f32_16x16x32_bf16 v[14:17], v[172:175], v[196:199], v[14:17]
	v_mfma_f32_16x16x32_bf16 v[6:9], v[164:167], v[218:221], v[6:9]
	v_mfma_f32_16x16x32_bf16 v[2:5], v[172:175], v[218:221], v[2:5]
	s_barrier
	s_add_i32 s62, s62, 2
	s_add_u32 s60, s60, 0x100
	s_addc_u32 s61, s61, 0
	s_add_u32 s34, s34, 0x100
	s_addc_u32 s35, s35, 0
	s_cmp_gt_u32 s62, 29
	s_cbranch_scc0 .LBB0_463
	v_lshl_or_b32 v158, s56, 8, v161
	v_ashrrev_i32_e32 v159, 31, v158
	s_branch .LBB0_459
.LBB0_472:
	v_mov_b32_e32 v228, 0x358637bd
	v_mov_b32_e32 v229, 0x260
	v_mov_b32_e32 v230, 0x3727c5ac
	v_mov_b32_e32 v231, 0x7ff
	v_mov_b32_e32 v232, 0xff
	v_mov_b32_e32 v233, 0x800
	v_mov_b32_e32 v234, 0x100
	v_mov_b32_e32 v235, 0x7f800000
	v_mov_b32_e32 v236, 0x7fc00000
	v_mov_b32_e32 v237, 0xff800000
	v_mov_b32_e32 v238, 0x600
	v_mov_b32_e32 v239, 0x42800000
	v_not_b32_e32 v240, 63
	v_mov_b32_e32 v241, 0x60000
	v_mov_b64_e32 v[242:243], 0x47
	s_waitcnt vmcnt(0)
	s_cmpk_gt_u32 s4, 0xff
	s_cbranch_scc1 .LBB0_474
	s_barrier

; #define GAS __attribute__((address_space(1)))
; __device__ __forceinline__ unsigned cvt_pk_bf16(float lo, float hi) { unsigned r; asm volatile("v_cvt_pk_bf16_f32 %0, %1, %2" : "=v"(r) : "v"(lo), "v"(hi)); return r; }
;     __device__ __forceinline__ void operator()(const f32x4 (&acc)[2][2][4][2], const Unit& u, int wr, int wc, int fr, int fq) const {
;     ...
;         for (int ai = 0; ai < 2; ++ai)
; #pragma unroll
;             for (int m = 0; m < 4; ++m) { GAS bf16_t* rowp = O + (size_t)(row0 + ai * HALF + m * 16) * ldc + col0;
; #pragma unroll
;                 for (int bj = 0; bj < 2; ++bj) { f32x4 v0 = acc[ai][bj][m][0] + bv[bj][0], v1 = acc[ai][bj][m][1] + bv[bj][1];
;                     if (ACT == 1) {
; #pragma unroll
;                         for (int j = 0; j < 4; ++j) { const float a = fmaxf(v0[j], 0.f), b = fmaxf(v1[j], 0.f); v0[j] = a * a; v1[j] = b * b; } }
;                     u32x4 w; w.x = cvt_pk_bf16(v0[0], v0[1]); w.y = cvt_pk_bf16(v0[2], v0[3]); w.z = cvt_pk_bf16(v1[0], v1[1]); w.w = cvt_pk_bf16(v1[2], v1[3]);
;                     *(GAS u32x4*)(rowp + bj * HALF) = w; } }
.LBB0_1486:
	v_lshl_add_u32 v158, s44, 8, v1
	v_pk_add_f32 v[122:123], v[122:123], v[232:233]
	v_ashrrev_i32_e32 v159, 31, v158
	v_pk_add_f32 v[126:127], v[126:127], v[228:229]
	v_pk_add_f32 v[124:125], v[124:125], v[234:235]
	v_max_f32_e32 v122, 0, v122
	v_lshlrev_b64 v[164:165], 14, v[158:159]
	v_pk_add_f32 v[128:129], v[128:129], v[230:231]
	v_mul_f32_e32 v159, v122, v122
	v_max_f32_e32 v122, 0, v127
	v_max_f32_e32 v123, 0, v123
	v_max_f32_e32 v124, 0, v124
	v_lshl_add_u64 v[164:165], s[10:11], 0, v[164:165]
	v_lshlrev_b64 v[166:167], 1, v[156:157]
	v_max_f32_e32 v126, 0, v126
	v_mul_f32_e32 v122, v122, v122
	v_mul_f32_e32 v127, v123, v123
	v_max_f32_e32 v123, 0, v128
	v_mul_f32_e32 v128, v124, v124
	v_max_f32_e32 v124, 0, v129
	v_max_f32_e32 v125, 0, v125
	v_pk_add_f32 v[114:115], v[114:115], v[240:241]
	v_lshl_add_u64 v[156:157], v[164:165], 0, v[166:167]
	v_mul_f32_e32 v126, v126, v126
	v_mul_f32_e32 v123, v123, v123
	v_mul_f32_e32 v124, v124, v124
	v_mul_f32_e32 v125, v125, v125
	v_cvt_pk_bf16_f32 v122, v126, v122
	v_pk_add_f32 v[118:119], v[118:119], v[236:237]
	v_pk_add_f32 v[116:117], v[116:117], v[242:243]
	v_max_f32_e32 v114, 0, v114
	v_cvt_pk_bf16_f32 v123, v123, v124
	v_cvt_pk_bf16_f32 v124, v159, v127
	v_cvt_pk_bf16_f32 v125, v128, v125
	global_store_dwordx4 v[156:157], v[122:125], off
	v_pk_add_f32 v[120:121], v[120:121], v[238:239]
	v_max_f32_e32 v115, 0, v115
	v_mul_f32_e32 v122, v114, v114
	v_max_f32_e32 v114, 0, v119
	v_max_f32_e32 v116, 0, v116
	v_max_f32_e32 v118, 0, v118
	v_mul_f32_e32 v114, v114, v114
	v_mul_f32_e32 v119, v115, v115
	v_max_f32_e32 v115, 0, v120
	v_mul_f32_e32 v120, v116, v116
	v_max_f32_e32 v116, 0, v121
	v_max_f32_e32 v117, 0, v117
	v_mul_f32_e32 v118, v118, v118
	v_mul_f32_e32 v115, v115, v115
	v_mul_f32_e32 v116, v116, v116
	v_mul_f32_e32 v117, v117, v117
	v_cvt_pk_bf16_f32 v114, v118, v114
	v_cvt_pk_bf16_f32 v115, v115, v116
	v_cvt_pk_bf16_f32 v116, v122, v119
	v_cvt_pk_bf16_f32 v117, v120, v117
	global_store_dwordx4 v[156:157], v[114:117], off offset:256
	v_pk_add_f32 v[106:107], v[106:107], v[232:233]
	v_pk_add_f32 v[110:111], v[110:111], v[228:229]
	v_or_b32_e32 v114, 16, v158
	v_ashrrev_i32_e32 v115, 31, v114
	v_pk_add_f32 v[108:109], v[108:109], v[234:235]
	v_max_f32_e32 v106, 0, v106
	v_lshlrev_b64 v[114:115], 14, v[114:115]
	v_pk_add_f32 v[112:113], v[112:113], v[230:231]
	v_mul_f32_e32 v116, v106, v106
	v_max_f32_e32 v106, 0, v111
	v_max_f32_e32 v107, 0, v107
	v_max_f32_e32 v108, 0, v108
	v_lshl_add_u64 v[114:115], s[10:11], 0, v[114:115]
	v_max_f32_e32 v110, 0, v110
	v_mul_f32_e32 v106, v106, v106
	v_mul_f32_e32 v111, v107, v107
	v_max_f32_e32 v107, 0, v112
	v_mul_f32_e32 v112, v108, v108
	v_max_f32_e32 v108, 0, v113
	v_max_f32_e32 v109, 0, v109
	v_pk_add_f32 v[98:99], v[98:99], v[240:241]
	v_lshl_add_u64 v[114:115], v[114:115], 0, v[166:167]
	v_mul_f32_e32 v110, v110, v110
	v_mul_f32_e32 v107, v107, v107
	v_mul_f32_e32 v108, v108, v108
	v_mul_f32_e32 v109, v109, v109
	v_cvt_pk_bf16_f32 v106, v110, v106
	v_pk_add_f32 v[102:103], v[102:103], v[236:237]
	v_pk_add_f32 v[100:101], v[100:101], v[242:243]
	v_max_f32_e32 v98, 0, v98
	v_cvt_pk_bf16_f32 v107, v107, v108
	v_cvt_pk_bf16_f32 v108, v116, v111
	v_cvt_pk_bf16_f32 v109, v112, v109
	global_store_dwordx4 v[114:115], v[106:109], off
	v_pk_add_f32 v[104:105], v[104:105], v[238:239]
	v_max_f32_e32 v99, 0, v99
	v_mul_f32_e32 v106, v98, v98
	v_max_f32_e32 v98, 0, v103
	v_max_f32_e32 v100, 0, v100
	v_max_f32_e32 v102, 0, v102
	v_mul_f32_e32 v98, v98, v98
	v_mul_f32_e32 v103, v99, v99
	v_max_f32_e32 v99, 0, v104
	v_mul_f32_e32 v104, v100, v100
	v_max_f32_e32 v100, 0, v105
	v_max_f32_e32 v101, 0, v101
	v_mul_f32_e32 v102, v102, v102
	v_mul_f32_e32 v99, v99, v99
	v_mul_f32_e32 v100, v100, v100
	v_mul_f32_e32 v101, v101, v101
	v_cvt_pk_bf16_f32 v98, v102, v98
	v_cvt_pk_bf16_f32 v99, v99, v100
	v_cvt_pk_bf16_f32 v100, v106, v103
	v_cvt_pk_bf16_f32 v101, v104, v101
	global_store_dwordx4 v[114:115], v[98:101], off offset:256
	v_pk_add_f32 v[90:91], v[90:91], v[232:233]
	v_pk_add_f32 v[94:95], v[94:95], v[228:229]
	v_or_b32_e32 v98, 32, v158
	v_ashrrev_i32_e32 v99, 31, v98
	v_pk_add_f32 v[92:93], v[92:93], v[234:235]
	v_max_f32_e32 v90, 0, v90
	v_lshlrev_b64 v[98:99], 14, v[98:99]
	v_pk_add_f32 v[96:97], v[96:97], v[230:231]
	v_mul_f32_e32 v100, v90, v90
	v_max_f32_e32 v90, 0, v95
	v_max_f32_e32 v91, 0, v91
	v_max_f32_e32 v92, 0, v92
	v_lshl_add_u64 v[98:99], s[10:11], 0, v[98:99]
	v_max_f32_e32 v94, 0, v94
	v_mul_f32_e32 v90, v90, v90
	v_mul_f32_e32 v95, v91, v91
	v_max_f32_e32 v91, 0, v96
	v_mul_f32_e32 v96, v92, v92
	v_max_f32_e32 v92, 0, v97
	v_max_f32_e32 v93, 0, v93
	v_pk_add_f32 v[82:83], v[82:83], v[240:241]
	v_lshl_add_u64 v[98:99], v[98:99], 0, v[166:167]
	v_mul_f32_e32 v94, v94, v94
	v_mul_f32_e32 v91, v91, v91
	v_mul_f32_e32 v92, v92, v92
	v_mul_f32_e32 v93, v93, v93
	v_cvt_pk_bf16_f32 v90, v94, v90
	v_pk_add_f32 v[86:87], v[86:87], v[236:237]
	v_pk_add_f32 v[84:85], v[84:85], v[242:243]
	v_max_f32_e32 v82, 0, v82
	v_cvt_pk_bf16_f32 v91, v91, v92
	v_cvt_pk_bf16_f32 v92, v100, v95
	v_cvt_pk_bf16_f32 v93, v96, v93
	global_store_dwordx4 v[98:99], v[90:93], off
	v_pk_add_f32 v[88:89], v[88:89], v[238:239]
	v_max_f32_e32 v83, 0, v83
	v_mul_f32_e32 v90, v82, v82
	v_max_f32_e32 v82, 0, v87
	v_max_f32_e32 v84, 0, v84
	v_max_f32_e32 v86, 0, v86
	v_mul_f32_e32 v82, v82, v82
	v_mul_f32_e32 v87, v83, v83
	v_max_f32_e32 v83, 0, v88
	v_mul_f32_e32 v88, v84, v84
	v_max_f32_e32 v84, 0, v89
	v_max_f32_e32 v85, 0, v85
	v_mul_f32_e32 v86, v86, v86
	v_mul_f32_e32 v83, v83, v83
	v_mul_f32_e32 v84, v84, v84
	v_mul_f32_e32 v85, v85, v85
	v_cvt_pk_bf16_f32 v82, v86, v82
; #define GAS __attribute__((address_space(1)))
; __device__ __forceinline__ unsigned cvt_pk_bf16(float lo, float hi) { unsigned r; asm volatile("v_cvt_pk_bf16_f32 %0, %1, %2" : "=v"(r) : "v"(lo), "v"(hi)); return r; }
;     __device__ __forceinline__ void operator()(const f32x4 (&acc)[2][2][4][2], const Unit& u, int wr, int wc, int fr, int fq) const {
;     ...
;         for (int ai = 0; ai < 2; ++ai)
; #pragma unroll
;             for (int m = 0; m < 4; ++m) { GAS bf16_t* rowp = O + (size_t)(row0 + ai * HALF + m * 16) * ldc + col0;
; #pragma unroll
;                 for (int bj = 0; bj < 2; ++bj) { f32x4 v0 = acc[ai][bj][m][0] + bv[bj][0], v1 = acc[ai][bj][m][1] + bv[bj][1];
;                     if (ACT == 1) {
; #pragma unroll
;                         for (int j = 0; j < 4; ++j) { const float a = fmaxf(v0[j], 0.f), b = fmaxf(v1[j], 0.f); v0[j] = a * a; v1[j] = b * b; } }
;                     u32x4 w; w.x = cvt_pk_bf16(v0[0], v0[1]); w.y = cvt_pk_bf16(v0[2], v0[3]); w.z = cvt_pk_bf16(v1[0], v1[1]); w.w = cvt_pk_bf16(v1[2], v1[3]);
;                     *(GAS u32x4*)(rowp + bj * HALF) = w; } }
	v_cvt_pk_bf16_f32 v83, v83, v84
	v_cvt_pk_bf16_f32 v84, v90, v87
	v_cvt_pk_bf16_f32 v85, v88, v85
	global_store_dwordx4 v[98:99], v[82:85], off offset:256
	v_pk_add_f32 v[74:75], v[74:75], v[232:233]
	v_pk_add_f32 v[78:79], v[78:79], v[228:229]
	v_or_b32_e32 v82, 48, v158
	v_ashrrev_i32_e32 v83, 31, v82
	v_pk_add_f32 v[76:77], v[76:77], v[234:235]
	v_max_f32_e32 v74, 0, v74
	v_lshlrev_b64 v[82:83], 14, v[82:83]
	v_pk_add_f32 v[80:81], v[80:81], v[230:231]
	v_mul_f32_e32 v84, v74, v74
	v_max_f32_e32 v74, 0, v79
	v_max_f32_e32 v75, 0, v75
	v_max_f32_e32 v76, 0, v76
	v_lshl_add_u64 v[82:83], s[10:11], 0, v[82:83]
	v_max_f32_e32 v78, 0, v78
	v_mul_f32_e32 v74, v74, v74
	v_mul_f32_e32 v79, v75, v75
	v_max_f32_e32 v75, 0, v80
	v_mul_f32_e32 v80, v76, v76
	v_max_f32_e32 v76, 0, v81
	v_max_f32_e32 v77, 0, v77
	v_pk_add_f32 v[68:69], v[68:69], v[242:243]
	v_pk_add_f32 v[66:67], v[66:67], v[240:241]
	v_lshl_add_u64 v[82:83], v[82:83], 0, v[166:167]
	v_mul_f32_e32 v78, v78, v78
	v_mul_f32_e32 v75, v75, v75
	v_mul_f32_e32 v76, v76, v76
	v_mul_f32_e32 v77, v77, v77
	v_cvt_pk_bf16_f32 v74, v78, v74
	v_pk_add_f32 v[72:73], v[72:73], v[238:239]
	v_pk_add_f32 v[70:71], v[70:71], v[236:237]
	v_max_f32_e32 v66, 0, v66
	v_max_f32_e32 v67, 0, v67
	v_max_f32_e32 v68, 0, v68
	v_cvt_pk_bf16_f32 v75, v75, v76
	v_cvt_pk_bf16_f32 v76, v84, v79
	v_cvt_pk_bf16_f32 v77, v80, v77
	global_store_dwordx4 v[82:83], v[74:77], off
	v_max_f32_e32 v70, 0, v70
	v_max_f32_e32 v69, 0, v69
	v_mul_f32_e32 v74, v66, v66
	v_max_f32_e32 v66, 0, v71
	v_mul_f32_e32 v71, v67, v67
	v_max_f32_e32 v67, 0, v72
	v_mul_f32_e32 v72, v68, v68
	v_max_f32_e32 v68, 0, v73
	v_mul_f32_e32 v66, v66, v66
	v_mul_f32_e32 v67, v67, v67
	v_mul_f32_e32 v68, v68, v68
	v_pk_add_f32 v[58:59], v[58:59], v[232:233]
	v_mul_f32_e32 v70, v70, v70
	v_mul_f32_e32 v69, v69, v69
	v_cvt_pk_bf16_f32 v66, v70, v66
	v_cvt_pk_bf16_f32 v67, v67, v68
	v_cvt_pk_bf16_f32 v68, v74, v71
	v_pk_add_f32 v[62:63], v[62:63], v[228:229]
	v_pk_add_f32 v[60:61], v[60:61], v[234:235]
	v_max_f32_e32 v58, 0, v58
	v_cvt_pk_bf16_f32 v69, v72, v69
	global_store_dwordx4 v[82:83], v[66:69], off offset:256
	v_pk_add_f32 v[64:65], v[64:65], v[230:231]
	v_max_f32_e32 v62, 0, v62
	v_mul_f32_e32 v68, v58, v58
	v_max_f32_e32 v58, 0, v63
	v_max_f32_e32 v59, 0, v59
	v_max_f32_e32 v60, 0, v60
	v_mul_f32_e32 v62, v62, v62
	v_mul_f32_e32 v58, v58, v58
	v_mul_f32_e32 v63, v59, v59
	v_max_f32_e32 v59, 0, v64
	v_mul_f32_e32 v64, v60, v60
	v_max_f32_e32 v60, 0, v65
	s_mov_b32 s25, 0x200000
	v_mul_f32_e32 v59, v59, v59
	v_max_f32_e32 v61, 0, v61
	v_mul_f32_e32 v60, v60, v60
	v_cvt_pk_bf16_f32 v58, v62, v58
	v_add_co_u32_e32 v62, vcc, s25, v156
	v_pk_add_f32 v[52:53], v[52:53], v[242:243]
	v_pk_add_f32 v[50:51], v[50:51], v[240:241]
	v_mul_f32_e32 v61, v61, v61
	v_cvt_pk_bf16_f32 v59, v59, v60
	v_cvt_pk_bf16_f32 v60, v68, v63
	v_addc_co_u32_e32 v63, vcc, 0, v157, vcc
	v_pk_add_f32 v[56:57], v[56:57], v[238:239]
	v_pk_add_f32 v[54:55], v[54:55], v[236:237]
	v_max_f32_e32 v50, 0, v50
	v_max_f32_e32 v51, 0, v51
	v_max_f32_e32 v52, 0, v52
	v_cvt_pk_bf16_f32 v61, v64, v61
	global_store_dwordx4 v[62:63], v[58:61], off
	s_mov_b64 s[42:43], 0x200000
	v_max_f32_e32 v54, 0, v54
	v_mul_f32_e32 v58, v50, v50
	v_max_f32_e32 v50, 0, v55
	v_mul_f32_e32 v55, v51, v51
	v_max_f32_e32 v51, 0, v56
	v_mul_f32_e32 v56, v52, v52
	v_max_f32_e32 v52, 0, v57
	v_mul_f32_e32 v50, v50, v50
	v_mul_f32_e32 v51, v51, v51
	v_max_f32_e32 v53, 0, v53
	v_mul_f32_e32 v52, v52, v52
	v_pk_add_f32 v[42:43], v[42:43], v[232:233]
	v_lshl_add_u64 v[66:67], v[156:157], 0, s[42:43]
	v_mul_f32_e32 v54, v54, v54
	v_mul_f32_e32 v53, v53, v53
	v_cvt_pk_bf16_f32 v50, v54, v50
	v_cvt_pk_bf16_f32 v51, v51, v52
	v_cvt_pk_bf16_f32 v52, v58, v55
	v_pk_add_f32 v[46:47], v[46:47], v[228:229]
	v_pk_add_f32 v[44:45], v[44:45], v[234:235]
	v_max_f32_e32 v42, 0, v42
	v_cvt_pk_bf16_f32 v53, v56, v53
	global_store_dwordx4 v[66:67], v[50:53], off offset:256
	v_pk_add_f32 v[48:49], v[48:49], v[230:231]
	v_max_f32_e32 v46, 0, v46
	v_mul_f32_e32 v52, v42, v42
	v_max_f32_e32 v42, 0, v47
	v_max_f32_e32 v43, 0, v43
	v_max_f32_e32 v44, 0, v44
	v_mul_f32_e32 v46, v46, v46
	v_mul_f32_e32 v42, v42, v42
	v_mul_f32_e32 v47, v43, v43
	v_max_f32_e32 v43, 0, v48
	v_mul_f32_e32 v48, v44, v44
	v_max_f32_e32 v44, 0, v49
	s_mov_b32 s25, 0x240000
	v_mul_f32_e32 v43, v43, v43
	v_max_f32_e32 v45, 0, v45
	v_mul_f32_e32 v44, v44, v44
	v_cvt_pk_bf16_f32 v42, v46, v42
	v_add_co_u32_e32 v46, vcc, s25, v156
	v_pk_add_f32 v[36:37], v[36:37], v[242:243]
	v_pk_add_f32 v[34:35], v[34:35], v[240:241]
	v_mul_f32_e32 v45, v45, v45
	v_cvt_pk_bf16_f32 v43, v43, v44
	v_cvt_pk_bf16_f32 v44, v52, v47
; #define GAS __attribute__((address_space(1)))
; __device__ __forceinline__ unsigned cvt_pk_bf16(float lo, float hi) { unsigned r; asm volatile("v_cvt_pk_bf16_f32 %0, %1, %2" : "=v"(r) : "v"(lo), "v"(hi)); return r; }
;     __device__ __forceinline__ void operator()(const f32x4 (&acc)[2][2][4][2], const Unit& u, int wr, int wc, int fr, int fq) const {
;     ...
;         for (int ai = 0; ai < 2; ++ai)
; #pragma unroll
;             for (int m = 0; m < 4; ++m) { GAS bf16_t* rowp = O + (size_t)(row0 + ai * HALF + m * 16) * ldc + col0;
; #pragma unroll
;                 for (int bj = 0; bj < 2; ++bj) { f32x4 v0 = acc[ai][bj][m][0] + bv[bj][0], v1 = acc[ai][bj][m][1] + bv[bj][1];
;                     if (ACT == 1) {
; #pragma unroll
;                         for (int j = 0; j < 4; ++j) { const float a = fmaxf(v0[j], 0.f), b = fmaxf(v1[j], 0.f); v0[j] = a * a; v1[j] = b * b; } }
;                     u32x4 w; w.x = cvt_pk_bf16(v0[0], v0[1]); w.y = cvt_pk_bf16(v0[2], v0[3]); w.z = cvt_pk_bf16(v1[0], v1[1]); w.w = cvt_pk_bf16(v1[2], v1[3]);
;                     *(GAS u32x4*)(rowp + bj * HALF) = w; } }
	v_addc_co_u32_e32 v47, vcc, 0, v157, vcc
	v_pk_add_f32 v[40:41], v[40:41], v[238:239]
	v_pk_add_f32 v[38:39], v[38:39], v[236:237]
	v_max_f32_e32 v34, 0, v34
	v_max_f32_e32 v35, 0, v35
	v_max_f32_e32 v36, 0, v36
	v_cvt_pk_bf16_f32 v45, v48, v45
	global_store_dwordx4 v[46:47], v[42:45], off
	s_mov_b64 s[42:43], 0x240000
	v_max_f32_e32 v38, 0, v38
	v_mul_f32_e32 v42, v34, v34
	v_max_f32_e32 v34, 0, v39
	v_mul_f32_e32 v39, v35, v35
	v_max_f32_e32 v35, 0, v40
	v_mul_f32_e32 v40, v36, v36
	v_max_f32_e32 v36, 0, v41
	v_mul_f32_e32 v34, v34, v34
	v_mul_f32_e32 v35, v35, v35
	v_max_f32_e32 v37, 0, v37
	v_mul_f32_e32 v36, v36, v36
	v_pk_add_f32 v[26:27], v[26:27], v[232:233]
	v_lshl_add_u64 v[50:51], v[156:157], 0, s[42:43]
	v_mul_f32_e32 v38, v38, v38
	v_mul_f32_e32 v37, v37, v37
	v_cvt_pk_bf16_f32 v34, v38, v34
	v_cvt_pk_bf16_f32 v35, v35, v36
	v_cvt_pk_bf16_f32 v36, v42, v39
	v_pk_add_f32 v[30:31], v[30:31], v[228:229]
	v_pk_add_f32 v[28:29], v[28:29], v[234:235]
	v_max_f32_e32 v26, 0, v26
	v_cvt_pk_bf16_f32 v37, v40, v37
	global_store_dwordx4 v[50:51], v[34:37], off offset:256
	v_pk_add_f32 v[32:33], v[32:33], v[230:231]
	v_max_f32_e32 v30, 0, v30
	v_mul_f32_e32 v36, v26, v26
	v_max_f32_e32 v26, 0, v31
	v_max_f32_e32 v27, 0, v27
	v_max_f32_e32 v28, 0, v28
	v_mul_f32_e32 v30, v30, v30
	v_mul_f32_e32 v26, v26, v26
	v_mul_f32_e32 v31, v27, v27
	v_max_f32_e32 v27, 0, v32
	v_mul_f32_e32 v32, v28, v28
	v_max_f32_e32 v28, 0, v33
	s_mov_b32 s25, 0x280000
	v_mul_f32_e32 v27, v27, v27
	v_max_f32_e32 v29, 0, v29
	v_mul_f32_e32 v28, v28, v28
	v_cvt_pk_bf16_f32 v26, v30, v26
	v_add_co_u32_e32 v30, vcc, s25, v156
	v_pk_add_f32 v[20:21], v[20:21], v[242:243]
	v_pk_add_f32 v[18:19], v[18:19], v[240:241]
	v_mul_f32_e32 v29, v29, v29
	v_cvt_pk_bf16_f32 v27, v27, v28
	v_cvt_pk_bf16_f32 v28, v36, v31
	v_addc_co_u32_e32 v31, vcc, 0, v157, vcc
	v_pk_add_f32 v[24:25], v[24:25], v[238:239]
	v_pk_add_f32 v[22:23], v[22:23], v[236:237]
	v_max_f32_e32 v18, 0, v18
	v_max_f32_e32 v19, 0, v19
	v_max_f32_e32 v20, 0, v20
	v_cvt_pk_bf16_f32 v29, v32, v29
	global_store_dwordx4 v[30:31], v[26:29], off
	s_mov_b64 s[42:43], 0x280000
	v_max_f32_e32 v22, 0, v22
	v_mul_f32_e32 v26, v18, v18
	v_max_f32_e32 v18, 0, v23
	v_mul_f32_e32 v23, v19, v19
	v_max_f32_e32 v19, 0, v24
	v_mul_f32_e32 v24, v20, v20
	v_max_f32_e32 v20, 0, v25
	v_mul_f32_e32 v18, v18, v18
	v_mul_f32_e32 v19, v19, v19
	v_max_f32_e32 v21, 0, v21
	v_mul_f32_e32 v20, v20, v20
	v_pk_add_f32 v[10:11], v[10:11], v[232:233]
	v_lshl_add_u64 v[34:35], v[156:157], 0, s[42:43]
	v_mul_f32_e32 v22, v22, v22
	v_mul_f32_e32 v21, v21, v21
	v_cvt_pk_bf16_f32 v18, v22, v18
	v_cvt_pk_bf16_f32 v19, v19, v20
	v_cvt_pk_bf16_f32 v20, v26, v23
	v_pk_add_f32 v[14:15], v[14:15], v[228:229]
	v_pk_add_f32 v[12:13], v[12:13], v[234:235]
	v_max_f32_e32 v10, 0, v10
	v_cvt_pk_bf16_f32 v21, v24, v21
	global_store_dwordx4 v[34:35], v[18:21], off offset:256
	v_pk_add_f32 v[16:17], v[16:17], v[230:231]
	v_max_f32_e32 v14, 0, v14
	v_mul_f32_e32 v20, v10, v10
	v_max_f32_e32 v10, 0, v15
	v_max_f32_e32 v11, 0, v11
	v_max_f32_e32 v12, 0, v12
	v_mul_f32_e32 v14, v14, v14
	v_mul_f32_e32 v10, v10, v10
	v_mul_f32_e32 v15, v11, v11
	v_max_f32_e32 v11, 0, v16
	v_mul_f32_e32 v16, v12, v12
	v_max_f32_e32 v12, 0, v17
	s_mov_b32 s25, 0x2c0000
	v_mul_f32_e32 v11, v11, v11
	v_max_f32_e32 v13, 0, v13
	v_mul_f32_e32 v12, v12, v12
	v_cvt_pk_bf16_f32 v10, v14, v10
	v_add_co_u32_e32 v14, vcc, s25, v156
	v_pk_add_f32 v[4:5], v[4:5], v[242:243]
	v_pk_add_f32 v[2:3], v[2:3], v[240:241]
	v_mul_f32_e32 v13, v13, v13
	v_cvt_pk_bf16_f32 v11, v11, v12
	v_cvt_pk_bf16_f32 v12, v20, v15
	v_addc_co_u32_e32 v15, vcc, 0, v157, vcc
	v_pk_add_f32 v[8:9], v[8:9], v[238:239]
	v_pk_add_f32 v[6:7], v[6:7], v[236:237]
	v_max_f32_e32 v2, 0, v2
	v_max_f32_e32 v3, 0, v3
	v_max_f32_e32 v4, 0, v4
	s_mov_b64 s[42:43], 0x2c0000
	v_cvt_pk_bf16_f32 v13, v16, v13
	global_store_dwordx4 v[14:15], v[10:13], off
	v_max_f32_e32 v5, 0, v5
	v_lshl_add_u64 v[18:19], v[156:157], 0, s[42:43]
	v_mul_f32_e32 v10, v2, v2
	v_max_f32_e32 v2, 0, v7
	v_mul_f32_e32 v7, v3, v3
	v_max_f32_e32 v3, 0, v8
	v_mul_f32_e32 v8, v4, v4
	v_max_f32_e32 v4, 0, v9
	v_max_f32_e32 v6, 0, v6
	v_mul_f32_e32 v2, v2, v2
	v_mul_f32_e32 v3, v3, v3
	v_mul_f32_e32 v4, v4, v4
	v_mul_f32_e32 v5, v5, v5
	s_and_b64 vcc, exec, s[40:41]
	s_mov_b32 s64, s24
	s_mov_b32 s44, s26
	s_mov_b64 s[42:43], s[38:39]
	s_mov_b64 s[46:47], s[34:35]
	v_mul_f32_e32 v6, v6, v6
	v_cvt_pk_bf16_f32 v2, v6, v2
	v_cvt_pk_bf16_f32 v3, v3, v4
	v_cvt_pk_bf16_f32 v4, v10, v7
	v_cvt_pk_bf16_f32 v5, v8, v5
	global_store_dwordx4 v[18:19], v[2:5], off offset:256
	s_cbranch_vccnz .LBB0_1499

; #define GAS __attribute__((address_space(1)))
; template <class Epi, class Sched, bool ALIGN_EPI, bool SP2>
; __device__ __forceinline__ void gemm_phase(LAS unsigned char* lds, const int tid, const Gemm g, const Sched& S, const Epi& E) {
;     ...
;         bool rst = true; if constexpr (Epi::KEEPS) rst = E.reset(cur);
;         if (rst) {
; #pragma unroll
;         for (int a = 0; a < 2; ++a)
; #pragma unroll
;             for (int b = 0; b < 2; ++b)
; #pragma unroll
;                 for (int m = 0; m < 4; ++m)
; #pragma unroll
;                     for (int n = 0; n < 2; ++n) acc[a][b][m][n] = (f32x4){0.f, 0.f, 0.f, 0.f};
;         }
;         cur = nxt; cA = nA; cB = nB; ++ui;
;     __device__ __forceinline__ void operator()(const f32x4 (&acc)[2][2][4][2], const Unit& u, int wr, int wc, int fr, int fq) const {
;     ...
;         for (int bj = 0; bj < 2; ++bj)
; #pragma unroll
;             for (int n = 0; n < 2; ++n) bv[bj][n] = bias ? *(const GAS f32x4*)(bias + col0 + bj * HALF + 4 * n) : (f32x4){0.f, 0.f, 0.f, 0.f};
.LBB0_1489:
	v_mov_b64_e32 v[2:3], s[8:9]
	s_ashr_i32 s27, s26, 31
	v_cmp_lt_i64_e32 vcc, s[34:35], v[2:3]
	s_lshl_b64 s[34:35], s[26:27], 20
	s_add_u32 s34, s52, s34
	s_addc_u32 s35, s53, s35
	s_and_b64 s[38:39], vcc, exec
	s_cselect_b32 s27, s35, s47
	s_cselect_b32 s65, s34, s46
	s_ashr_i32 s25, s24, 31
	s_lshl_b64 s[38:39], s[24:25], 20
	s_add_u32 s38, s54, s38
	s_addc_u32 s39, s55, s39
	s_and_b64 s[48:49], vcc, exec
	s_cselect_b32 s25, s39, s43
	s_cselect_b32 s68, s38, s42
	s_add_u32 s69, s42, 0x100
	s_addc_u32 s70, s43, 0
	s_add_u32 s42, s46, 0x80080
	v_lshl_or_b32 v156, s64, 8, v161
	v_ashrrev_i32_e32 v157, 31, v156
	v_lshl_add_u64 v[158:159], v[156:157], 2, s[18:19]
	global_load_dwordx4 v[228:231], v[158:159], off
	global_load_dwordx4 v[232:235], v[158:159], off offset:16
	global_load_dwordx4 v[236:239], v[158:159], off offset:512
	global_load_dwordx4 v[240:243], v[158:159], off offset:528
	v_mov_b32_e32 v2, 0
	s_addc_u32 s43, s47, 0
	s_mov_b32 s71, -2
	v_mov_b32_e32 v3, v2
	v_mov_b32_e32 v4, v2
	v_mov_b32_e32 v5, v2
	v_mov_b32_e32 v6, v2
	v_mov_b32_e32 v7, v2
	v_mov_b32_e32 v8, v2
	v_mov_b32_e32 v9, v2
	v_mov_b32_e32 v18, v2
	v_mov_b32_e32 v19, v2
	v_mov_b32_e32 v20, v2
	v_mov_b32_e32 v21, v2
	v_mov_b32_e32 v22, v2
	v_mov_b32_e32 v23, v2
	v_mov_b32_e32 v24, v2
	v_mov_b32_e32 v25, v2
	v_mov_b32_e32 v34, v2
	v_mov_b32_e32 v35, v2
	v_mov_b32_e32 v36, v2
	v_mov_b32_e32 v37, v2
	v_mov_b32_e32 v38, v2
	v_mov_b32_e32 v39, v2
	v_mov_b32_e32 v40, v2
	v_mov_b32_e32 v41, v2
	v_mov_b32_e32 v50, v2
	v_mov_b32_e32 v51, v2
	v_mov_b32_e32 v52, v2
	v_mov_b32_e32 v53, v2
	v_mov_b32_e32 v54, v2
	v_mov_b32_e32 v55, v2
	v_mov_b32_e32 v56, v2
	v_mov_b32_e32 v57, v2
	v_mov_b32_e32 v10, v2
	v_mov_b32_e32 v11, v2
	v_mov_b32_e32 v12, v2
	v_mov_b32_e32 v13, v2
	v_mov_b32_e32 v14, v2
	v_mov_b32_e32 v15, v2
	v_mov_b32_e32 v16, v2
	v_mov_b32_e32 v17, v2
	v_mov_b32_e32 v26, v2
	v_mov_b32_e32 v27, v2
	v_mov_b32_e32 v28, v2
	v_mov_b32_e32 v29, v2
	v_mov_b32_e32 v30, v2
	v_mov_b32_e32 v31, v2
	v_mov_b32_e32 v32, v2
	v_mov_b32_e32 v33, v2
	v_mov_b32_e32 v42, v2
	v_mov_b32_e32 v43, v2
	v_mov_b32_e32 v44, v2
	v_mov_b32_e32 v45, v2
	v_mov_b32_e32 v46, v2
	v_mov_b32_e32 v47, v2
	v_mov_b32_e32 v48, v2
	v_mov_b32_e32 v49, v2
	v_mov_b32_e32 v58, v2
	v_mov_b32_e32 v59, v2
	v_mov_b32_e32 v60, v2
	v_mov_b32_e32 v61, v2
	v_mov_b32_e32 v62, v2
	v_mov_b32_e32 v63, v2
	v_mov_b32_e32 v64, v2
	v_mov_b32_e32 v65, v2
	v_mov_b32_e32 v66, v2
	v_mov_b32_e32 v67, v2
	v_mov_b32_e32 v68, v2
	v_mov_b32_e32 v69, v2
	v_mov_b32_e32 v70, v2
	v_mov_b32_e32 v71, v2
	v_mov_b32_e32 v72, v2
	v_mov_b32_e32 v73, v2
	v_mov_b32_e32 v82, v2
	v_mov_b32_e32 v83, v2
	v_mov_b32_e32 v84, v2
	v_mov_b32_e32 v85, v2
	v_mov_b32_e32 v86, v2
	v_mov_b32_e32 v87, v2
	v_mov_b32_e32 v88, v2
	v_mov_b32_e32 v89, v2
	v_mov_b32_e32 v98, v2
	v_mov_b32_e32 v99, v2
	v_mov_b32_e32 v100, v2
	v_mov_b32_e32 v101, v2
	v_mov_b32_e32 v102, v2
	v_mov_b32_e32 v103, v2
	v_mov_b32_e32 v104, v2
	v_mov_b32_e32 v105, v2
	v_mov_b32_e32 v114, v2
	v_mov_b32_e32 v115, v2
	v_mov_b32_e32 v116, v2
	v_mov_b32_e32 v117, v2
	v_mov_b32_e32 v118, v2
	v_mov_b32_e32 v119, v2
	v_mov_b32_e32 v120, v2
	v_mov_b32_e32 v121, v2
	v_mov_b32_e32 v74, v2
	v_mov_b32_e32 v75, v2
	v_mov_b32_e32 v76, v2
	v_mov_b32_e32 v77, v2
	v_mov_b32_e32 v78, v2
	v_mov_b32_e32 v79, v2
	v_mov_b32_e32 v80, v2
	v_mov_b32_e32 v81, v2
	v_mov_b32_e32 v90, v2
	v_mov_b32_e32 v91, v2
	v_mov_b32_e32 v92, v2
	v_mov_b32_e32 v93, v2
	v_mov_b32_e32 v94, v2
	v_mov_b32_e32 v95, v2
	v_mov_b32_e32 v96, v2
	v_mov_b32_e32 v97, v2
	v_mov_b32_e32 v106, v2
	v_mov_b32_e32 v107, v2
	v_mov_b32_e32 v108, v2
	v_mov_b32_e32 v109, v2
	v_mov_b32_e32 v110, v2
	v_mov_b32_e32 v111, v2
	v_mov_b32_e32 v112, v2
	v_mov_b32_e32 v113, v2
	v_mov_b32_e32 v122, v2
	v_mov_b32_e32 v123, v2
	v_mov_b32_e32 v124, v2
	v_mov_b32_e32 v125, v2
	v_mov_b32_e32 v126, v2
	v_mov_b32_e32 v127, v2
	v_mov_b32_e32 v128, v2
	v_mov_b32_e32 v129, v2
.LBB0_1490:
	s_add_u32 s46, s42, 0xfff80080
	s_addc_u32 s47, s43, -1
	s_add_i32 s72, 0, 0x10000
	s_cmp_eq_u32 s71, 28
	s_cselect_b32 s49, s27, s47
	s_cselect_b32 s48, s65, s46
	s_cselect_b32 s47, s25, s70
	s_cselect_b32 s46, s68, s69
	s_add_i32 s82, 0, 0x14000
	v_add_u32_e32 v142, s72, v160
	v_add_u32_e32 v163, s82, v160
	ds_read_b128 v[130:133], v142
	ds_read_b128 v[134:137], v142 offset:1024
	ds_read_b128 v[138:141], v142 offset:2048
	ds_read_b128 v[142:145], v142 offset:3072
	ds_read_b128 v[156:159], v163
	ds_read_b128 v[164:167], v163 offset:1024
	ds_read_b128 v[168:171], v163 offset:2048
	ds_read_b128 v[172:175], v163 offset:3072
	v_lshl_add_u64 v[200:201], s[42:43], 0, v[154:155]
	s_add_i32 m0, s45, 0xc000
	ds_read_b128 v[176:179], v162
	ds_read_b128 v[180:183], v162 offset:1024
	ds_read_b128 v[184:187], v162 offset:2048
	ds_read_b128 v[188:191], v162 offset:3072
	ds_read_b128 v[192:195], v162 offset:4096
	ds_read_b128 v[196:199], v162 offset:5120
	ds_read_b128 v[214:217], v162 offset:6144
	ds_read_b128 v[218:221], v162 offset:7168
	global_load_lds_dwordx4 v[200:201], off
	v_lshl_add_u64 v[200:201], s[42:43], 0, v[152:153]
	s_add_i32 m0, s45, 0xe000
	s_nop 0
	global_load_lds_dwordx4 v[200:201], off
	s_waitcnt vmcnt(8)
	s_waitcnt lgkmcnt(0)
	s_barrier
; #define PG8_STAGE(bufoff, gbase, voff) do { _Pragma("unroll") for (int _i = 0; _i < 2; ++_i) \
;         __builtin_amdgcn_global_load_lds((const GAS unsigned*)((const GAS char*)(gbase) + (voff)[_i]), (LAS unsigned*)(lds + (bufoff) + ldsw + _i * 8192), 16, 0, 0); } while (0)
; #define PG8_LDA(dst, b, h) do { _Pragma("unroll") for (int m = 0; m < 4; ++m) _Pragma("unroll") for (int k = 0; k < 2; ++k) dst[m][k] = *(const LAS bf16x8*)(lds + PG8_SA(b, h) + aoff + m * 2048 + k * 1024); } while (0)
; #define PG8_LDB(dst, b, h) do { _Pragma("unroll") for (int n = 0; n < 2; ++n) _Pragma("unroll") for (int k = 0; k < 2; ++k) dst[n][k] = *(const LAS bf16x8*)(lds + PG8_SB(b, h) + boff + n * 2048 + k * 1024); } while (0)
; #define PG8_MMA(ai, bj, At, Bt) do { __builtin_amdgcn_sched_barrier(0); _Pragma("unroll") for (int m = 0; m < 4; ++m) _Pragma("unroll") for (int n = 0; n < 2; ++n) _Pragma("unroll") for (int k = 0; k < 2; ++k) \
;         acc[ai][bj][m][n] = __builtin_amdgcn_mfma_f32_16x16x32_bf16(Bt[n][k], At[m][k], acc[ai][bj][m][n], 0, 0, 0); __builtin_amdgcn_sched_barrier(0); } while (0)
; #define PG8_WAIT_V(n) asm volatile("s_waitcnt vmcnt(" #n ")" ::: "memory")
; #define PG8_WAIT_L(n) asm volatile("s_waitcnt lgkmcnt(" #n ")" ::: "memory")
; #define PG8_BAR __builtin_amdgcn_s_barrier()
; #define PG8_SCHED __builtin_amdgcn_sched_barrier(0)
; template <class Epi, class Sched, bool ALIGN_EPI, bool SP2>
; __device__ __forceinline__ void gemm_phase(LAS unsigned char* lds, const int tid, const Gemm g, const Sched& S, const Epi& E) {
;     ...
;             PG8_LDB(B0, 0, 0); PG8_LDB(B1, 0, 1); PG8_SCHED; PG8_LDA(At, 0, 0); PG8_STAGE(PG8_SA(1, 1), a1 + hstepA, voffA);
;             PG8_WAIT_V(8); PG8_WAIT_L(0); PG8_BAR; PG8_MMA(0, 0, At, B0); PG8_MMA(0, 1, At, B1); PG8_BAR; PG8_SCHED;
;             PG8_LDA(At, 0, 1); PG8_STAGE(PG8_SB(0, 0), b2, voffB); PG8_STAGE(PG8_SB(0, 1), b2 + hstepB, voffB); PG8_STAGE(PG8_SA(0, 0), a2, voffA);
;             PG8_WAIT_V(8); PG8_WAIT_L(0); PG8_BAR; PG8_MMA(1, 0, At, B0); PG8_MMA(1, 1, At, B1); PG8_BAR; PG8_SCHED;
;             PG8_LDB(B0, 1, 0); PG8_LDB(B1, 1, 1); PG8_SCHED; PG8_LDA(At, 1, 0); PG8_STAGE(PG8_SA(0, 1), a2 + hstepA, voffA);
;             PG8_WAIT_V(8); PG8_WAIT_L(0); PG8_BAR; PG8_MMA(0, 0, At, B0); PG8_MMA(0, 1, At, B1); PG8_BAR; PG8_SCHED;
	s_waitcnt lgkmcnt(0)
	v_mfma_f32_16x16x32_bf16 v[126:129], v[130:133], v[176:179], v[126:129]
	v_mfma_f32_16x16x32_bf16 v[122:125], v[138:141], v[176:179], v[122:125]
	v_mfma_f32_16x16x32_bf16 v[110:113], v[130:133], v[184:187], v[110:113]
	v_mfma_f32_16x16x32_bf16 v[106:109], v[138:141], v[184:187], v[106:109]
	v_mfma_f32_16x16x32_bf16 v[94:97], v[130:133], v[192:195], v[94:97]
	v_mfma_f32_16x16x32_bf16 v[90:93], v[138:141], v[192:195], v[90:93]
	v_mfma_f32_16x16x32_bf16 v[78:81], v[130:133], v[214:217], v[78:81]
	v_mfma_f32_16x16x32_bf16 v[74:77], v[138:141], v[214:217], v[74:77]
	v_mfma_f32_16x16x32_bf16 v[126:129], v[134:137], v[180:183], v[126:129]
	v_mfma_f32_16x16x32_bf16 v[122:125], v[142:145], v[180:183], v[122:125]
	v_mfma_f32_16x16x32_bf16 v[110:113], v[134:137], v[188:191], v[110:113]
	v_mfma_f32_16x16x32_bf16 v[106:109], v[142:145], v[188:191], v[106:109]
	v_mfma_f32_16x16x32_bf16 v[94:97], v[134:137], v[196:199], v[94:97]
	v_mfma_f32_16x16x32_bf16 v[90:93], v[142:145], v[196:199], v[90:93]
	v_mfma_f32_16x16x32_bf16 v[78:81], v[134:137], v[218:221], v[78:81]
	v_mfma_f32_16x16x32_bf16 v[74:77], v[142:145], v[218:221], v[74:77]
	v_mfma_f32_16x16x32_bf16 v[118:121], v[156:159], v[176:179], v[118:121]
	v_mfma_f32_16x16x32_bf16 v[114:117], v[168:171], v[176:179], v[114:117]
	v_mfma_f32_16x16x32_bf16 v[102:105], v[156:159], v[184:187], v[102:105]
	v_mfma_f32_16x16x32_bf16 v[98:101], v[168:171], v[184:187], v[98:101]
	v_mfma_f32_16x16x32_bf16 v[86:89], v[156:159], v[192:195], v[86:89]
	v_mfma_f32_16x16x32_bf16 v[82:85], v[168:171], v[192:195], v[82:85]
	v_mfma_f32_16x16x32_bf16 v[70:73], v[156:159], v[214:217], v[70:73]
	v_mfma_f32_16x16x32_bf16 v[66:69], v[168:171], v[214:217], v[66:69]
	v_mfma_f32_16x16x32_bf16 v[118:121], v[164:167], v[180:183], v[118:121]
	v_mfma_f32_16x16x32_bf16 v[114:117], v[172:175], v[180:183], v[114:117]
	v_mfma_f32_16x16x32_bf16 v[102:105], v[164:167], v[188:191], v[102:105]
	v_mfma_f32_16x16x32_bf16 v[98:101], v[172:175], v[188:191], v[98:101]
	v_mfma_f32_16x16x32_bf16 v[86:89], v[164:167], v[196:199], v[86:89]
	v_mfma_f32_16x16x32_bf16 v[82:85], v[172:175], v[196:199], v[82:85]
	v_mfma_f32_16x16x32_bf16 v[70:73], v[164:167], v[218:221], v[70:73]
	v_mfma_f32_16x16x32_bf16 v[66:69], v[172:175], v[218:221], v[66:69]
	s_barrier
	s_add_i32 s72, s72, s58
	v_lshl_add_u64 v[200:201], s[46:47], 0, v[202:203]
	s_mov_b32 m0, s72
	ds_read_b128 v[176:179], v162 offset:16384
	ds_read_b128 v[180:183], v162 offset:17408
	ds_read_b128 v[184:187], v162 offset:18432
	ds_read_b128 v[188:191], v162 offset:19456
	ds_read_b128 v[192:195], v162 offset:20480
	ds_read_b128 v[196:199], v162 offset:21504
	ds_read_b128 v[214:217], v162 offset:22528
	ds_read_b128 v[218:221], v162 offset:23552
	global_load_lds_dwordx4 v[200:201], off
	s_add_i32 m0, s72, 0x2000
	s_add_u32 s72, s46, 0x80000
	v_lshl_add_u64 v[222:223], s[46:47], 0, v[150:151]
	s_addc_u32 s73, s47, 0
	s_add_i32 s82, s82, s58
	global_load_lds_dwordx4 v[222:223], off
	v_lshl_add_u64 v[224:225], s[72:73], 0, v[202:203]
	s_mov_b32 m0, s82
	v_lshl_add_u64 v[226:227], s[48:49], 0, v[148:149]
	global_load_lds_dwordx4 v[224:225], off
	v_lshl_add_u64 v[224:225], s[72:73], 0, v[150:151]
	s_add_i32 m0, s82, 0x2000
	s_nop 0
	global_load_lds_dwordx4 v[224:225], off
	v_lshl_add_u64 v[224:225], s[48:49], 0, v[146:147]
	s_mov_b32 m0, s45
	s_nop 0
	global_load_lds_dwordx4 v[224:225], off
	s_mov_b32 m0, s59
	s_nop 0
	global_load_lds_dwordx4 v[226:227], off
	s_waitcnt vmcnt(8)
	s_waitcnt lgkmcnt(0)
	s_barrier
	s_waitcnt lgkmcnt(0)
	v_mfma_f32_16x16x32_bf16 v[62:65], v[130:133], v[176:179], v[62:65]
	v_mfma_f32_16x16x32_bf16 v[58:61], v[138:141], v[176:179], v[58:61]
	v_mfma_f32_16x16x32_bf16 v[46:49], v[130:133], v[184:187], v[46:49]
	v_mfma_f32_16x16x32_bf16 v[42:45], v[138:141], v[184:187], v[42:45]
	v_mfma_f32_16x16x32_bf16 v[30:33], v[130:133], v[192:195], v[30:33]
	v_mfma_f32_16x16x32_bf16 v[26:29], v[138:141], v[192:195], v[26:29]
	v_mfma_f32_16x16x32_bf16 v[14:17], v[130:133], v[214:217], v[14:17]
	v_mfma_f32_16x16x32_bf16 v[10:13], v[138:141], v[214:217], v[10:13]
	v_mfma_f32_16x16x32_bf16 v[62:65], v[134:137], v[180:183], v[62:65]
	v_mfma_f32_16x16x32_bf16 v[58:61], v[142:145], v[180:183], v[58:61]
	v_mfma_f32_16x16x32_bf16 v[46:49], v[134:137], v[188:191], v[46:49]
	v_mfma_f32_16x16x32_bf16 v[42:45], v[142:145], v[188:191], v[42:45]
	v_mfma_f32_16x16x32_bf16 v[30:33], v[134:137], v[196:199], v[30:33]
	v_mfma_f32_16x16x32_bf16 v[26:29], v[142:145], v[196:199], v[26:29]
	v_mfma_f32_16x16x32_bf16 v[14:17], v[134:137], v[218:221], v[14:17]
	v_mfma_f32_16x16x32_bf16 v[10:13], v[142:145], v[218:221], v[10:13]
	v_mfma_f32_16x16x32_bf16 v[54:57], v[156:159], v[176:179], v[54:57]
	v_mfma_f32_16x16x32_bf16 v[50:53], v[168:171], v[176:179], v[50:53]
	v_mfma_f32_16x16x32_bf16 v[38:41], v[156:159], v[184:187], v[38:41]
	v_mfma_f32_16x16x32_bf16 v[34:37], v[168:171], v[184:187], v[34:37]
	v_mfma_f32_16x16x32_bf16 v[22:25], v[156:159], v[192:195], v[22:25]
	v_mfma_f32_16x16x32_bf16 v[18:21], v[168:171], v[192:195], v[18:21]
	v_mfma_f32_16x16x32_bf16 v[6:9], v[156:159], v[214:217], v[6:9]
	v_mfma_f32_16x16x32_bf16 v[2:5], v[168:171], v[214:217], v[2:5]
	v_mfma_f32_16x16x32_bf16 v[54:57], v[164:167], v[180:183], v[54:57]
	v_mfma_f32_16x16x32_bf16 v[50:53], v[172:175], v[180:183], v[50:53]
	v_mfma_f32_16x16x32_bf16 v[38:41], v[164:167], v[188:191], v[38:41]
	v_mfma_f32_16x16x32_bf16 v[34:37], v[172:175], v[188:191], v[34:37]
	v_mfma_f32_16x16x32_bf16 v[22:25], v[164:167], v[196:199], v[22:25]
	v_mfma_f32_16x16x32_bf16 v[18:21], v[172:175], v[196:199], v[18:21]
	v_mfma_f32_16x16x32_bf16 v[6:9], v[164:167], v[218:221], v[6:9]
	v_mfma_f32_16x16x32_bf16 v[2:5], v[172:175], v[218:221], v[2:5]
	s_barrier
; #define PG8_STAGE(bufoff, gbase, voff) do { _Pragma("unroll") for (int _i = 0; _i < 2; ++_i) \
;         __builtin_amdgcn_global_load_lds((const GAS unsigned*)((const GAS char*)(gbase) + (voff)[_i]), (LAS unsigned*)(lds + (bufoff) + ldsw + _i * 8192), 16, 0, 0); } while (0)
; #define PG8_LDA(dst, b, h) do { _Pragma("unroll") for (int m = 0; m < 4; ++m) _Pragma("unroll") for (int k = 0; k < 2; ++k) dst[m][k] = *(const LAS bf16x8*)(lds + PG8_SA(b, h) + aoff + m * 2048 + k * 1024); } while (0)
; #define PG8_LDB(dst, b, h) do { _Pragma("unroll") for (int n = 0; n < 2; ++n) _Pragma("unroll") for (int k = 0; k < 2; ++k) dst[n][k] = *(const LAS bf16x8*)(lds + PG8_SB(b, h) + boff + n * 2048 + k * 1024); } while (0)
; #define PG8_MMA(ai, bj, At, Bt) do { __builtin_amdgcn_sched_barrier(0); _Pragma("unroll") for (int m = 0; m < 4; ++m) _Pragma("unroll") for (int n = 0; n < 2; ++n) _Pragma("unroll") for (int k = 0; k < 2; ++k) \
;         acc[ai][bj][m][n] = __builtin_amdgcn_mfma_f32_16x16x32_bf16(Bt[n][k], At[m][k], acc[ai][bj][m][n], 0, 0, 0); __builtin_amdgcn_sched_barrier(0); } while (0)
; #define PG8_WAIT_V(n) asm volatile("s_waitcnt vmcnt(" #n ")" ::: "memory")
; #define PG8_WAIT_L(n) asm volatile("s_waitcnt lgkmcnt(" #n ")" ::: "memory")
; #define PG8_BAR __builtin_amdgcn_s_barrier()
; #define PG8_SCHED __builtin_amdgcn_sched_barrier(0)
; template <class Epi, class Sched, bool ALIGN_EPI, bool SP2>
; __device__ __forceinline__ void gemm_phase(LAS unsigned char* lds, const int tid, const Gemm g, const Sched& S, const Epi& E) {
;     ...
;             PG8_LDB(B0, 1, 0); PG8_LDB(B1, 1, 1); PG8_SCHED; PG8_LDA(At, 1, 0); PG8_STAGE(PG8_SA(0, 1), a2 + hstepA, voffA);
;             PG8_WAIT_V(8); PG8_WAIT_L(0); PG8_BAR; PG8_MMA(0, 0, At, B0); PG8_MMA(0, 1, At, B1); PG8_BAR; PG8_SCHED;
	s_add_i32 s72, 0, 0x18000
	s_add_i32 s73, 0, 0x1c000
	v_add_u32_e32 v142, s72, v160
	v_add_u32_e32 v163, s73, v160
	ds_read_b128 v[130:133], v142
	ds_read_b128 v[134:137], v142 offset:1024
	ds_read_b128 v[138:141], v142 offset:2048
	ds_read_b128 v[142:145], v142 offset:3072
	ds_read_b128 v[156:159], v163
	ds_read_b128 v[164:167], v163 offset:1024
	ds_read_b128 v[168:171], v163 offset:2048
	ds_read_b128 v[172:175], v163 offset:3072
	s_add_u32 s48, s48, 0x80000
	s_addc_u32 s49, s49, 0
	s_mov_b32 m0, s60
	v_lshl_add_u64 v[246:247], s[48:49], 0, v[146:147]
	ds_read_b128 v[176:179], v162 offset:32768
	ds_read_b128 v[180:183], v162 offset:33792
	ds_read_b128 v[184:187], v162 offset:34816
	ds_read_b128 v[188:191], v162 offset:35840
	ds_read_b128 v[192:195], v162 offset:36864
	ds_read_b128 v[196:199], v162 offset:37888
	ds_read_b128 v[214:217], v162 offset:38912
	ds_read_b128 v[218:221], v162 offset:39936
	global_load_lds_dwordx4 v[246:247], off
	v_lshl_add_u64 v[246:247], s[48:49], 0, v[148:149]
	s_mov_b32 m0, s61
	s_nop 0
	global_load_lds_dwordx4 v[246:247], off
	s_waitcnt vmcnt(8)
	s_waitcnt lgkmcnt(0)
	s_barrier
	s_waitcnt lgkmcnt(0)
	v_mfma_f32_16x16x32_bf16 v[126:129], v[130:133], v[176:179], v[126:129]
	v_mfma_f32_16x16x32_bf16 v[122:125], v[138:141], v[176:179], v[122:125]
	v_mfma_f32_16x16x32_bf16 v[110:113], v[130:133], v[184:187], v[110:113]
	v_mfma_f32_16x16x32_bf16 v[106:109], v[138:141], v[184:187], v[106:109]
	v_mfma_f32_16x16x32_bf16 v[94:97], v[130:133], v[192:195], v[94:97]
	v_mfma_f32_16x16x32_bf16 v[90:93], v[138:141], v[192:195], v[90:93]
	v_mfma_f32_16x16x32_bf16 v[78:81], v[130:133], v[214:217], v[78:81]
	v_mfma_f32_16x16x32_bf16 v[74:77], v[138:141], v[214:217], v[74:77]
	v_mfma_f32_16x16x32_bf16 v[126:129], v[134:137], v[180:183], v[126:129]
	v_mfma_f32_16x16x32_bf16 v[122:125], v[142:145], v[180:183], v[122:125]
	v_mfma_f32_16x16x32_bf16 v[110:113], v[134:137], v[188:191], v[110:113]
	v_mfma_f32_16x16x32_bf16 v[106:109], v[142:145], v[188:191], v[106:109]
	v_mfma_f32_16x16x32_bf16 v[94:97], v[134:137], v[196:199], v[94:97]
	v_mfma_f32_16x16x32_bf16 v[90:93], v[142:145], v[196:199], v[90:93]
	v_mfma_f32_16x16x32_bf16 v[78:81], v[134:137], v[218:221], v[78:81]
	v_mfma_f32_16x16x32_bf16 v[74:77], v[142:145], v[218:221], v[74:77]
	v_mfma_f32_16x16x32_bf16 v[118:121], v[156:159], v[176:179], v[118:121]
	v_mfma_f32_16x16x32_bf16 v[114:117], v[168:171], v[176:179], v[114:117]
	v_mfma_f32_16x16x32_bf16 v[102:105], v[156:159], v[184:187], v[102:105]
	v_mfma_f32_16x16x32_bf16 v[98:101], v[168:171], v[184:187], v[98:101]
	v_mfma_f32_16x16x32_bf16 v[86:89], v[156:159], v[192:195], v[86:89]
	v_mfma_f32_16x16x32_bf16 v[82:85], v[168:171], v[192:195], v[82:85]
	v_mfma_f32_16x16x32_bf16 v[70:73], v[156:159], v[214:217], v[70:73]
	v_mfma_f32_16x16x32_bf16 v[66:69], v[168:171], v[214:217], v[66:69]
	v_mfma_f32_16x16x32_bf16 v[118:121], v[164:167], v[180:183], v[118:121]
	v_mfma_f32_16x16x32_bf16 v[114:117], v[172:175], v[180:183], v[114:117]
	v_mfma_f32_16x16x32_bf16 v[102:105], v[164:167], v[188:191], v[102:105]
	v_mfma_f32_16x16x32_bf16 v[98:101], v[172:175], v[188:191], v[98:101]
	v_mfma_f32_16x16x32_bf16 v[86:89], v[164:167], v[196:199], v[86:89]
	v_mfma_f32_16x16x32_bf16 v[82:85], v[172:175], v[196:199], v[82:85]
	v_mfma_f32_16x16x32_bf16 v[70:73], v[164:167], v[218:221], v[70:73]
	v_mfma_f32_16x16x32_bf16 v[66:69], v[172:175], v[218:221], v[66:69]
	s_barrier
; #define PG8_STAGE(bufoff, gbase, voff) do { _Pragma("unroll") for (int _i = 0; _i < 2; ++_i) \
;         __builtin_amdgcn_global_load_lds((const GAS unsigned*)((const GAS char*)(gbase) + (voff)[_i]), (LAS unsigned*)(lds + (bufoff) + ldsw + _i * 8192), 16, 0, 0); } while (0)
; #define PG8_LDA(dst, b, h) do { _Pragma("unroll") for (int m = 0; m < 4; ++m) _Pragma("unroll") for (int k = 0; k < 2; ++k) dst[m][k] = *(const LAS bf16x8*)(lds + PG8_SA(b, h) + aoff + m * 2048 + k * 1024); } while (0)
; #define PG8_MMA(ai, bj, At, Bt) do { __builtin_amdgcn_sched_barrier(0); _Pragma("unroll") for (int m = 0; m < 4; ++m) _Pragma("unroll") for (int n = 0; n < 2; ++n) _Pragma("unroll") for (int k = 0; k < 2; ++k) \
;         acc[ai][bj][m][n] = __builtin_amdgcn_mfma_f32_16x16x32_bf16(Bt[n][k], At[m][k], acc[ai][bj][m][n], 0, 0, 0); __builtin_amdgcn_sched_barrier(0); } while (0)
; #define PG8_WAIT_V(n) asm volatile("s_waitcnt vmcnt(" #n ")" ::: "memory")
; #define PG8_WAIT_L(n) asm volatile("s_waitcnt lgkmcnt(" #n ")" ::: "memory")
; #define PG8_BAR __builtin_amdgcn_s_barrier()
; #define PG8_SCHED __builtin_amdgcn_sched_barrier(0)
; template <class Epi, class Sched, bool ALIGN_EPI, bool SP2>
; __device__ __forceinline__ void gemm_phase(LAS unsigned char* lds, const int tid, const Gemm g, const Sched& S, const Epi& E) {
;     ...
;             PG8_LDA(At, 1, 1); PG8_STAGE(PG8_SB(1, 0), b3, voffB); PG8_STAGE(PG8_SB(1, 1), b3 + hstepB, voffB); PG8_STAGE(PG8_SA(1, 0), a3, voffA);
;             PG8_WAIT_V(8); PG8_WAIT_L(0); PG8_BAR; PG8_MMA(1, 0, At, B0); PG8_MMA(1, 1, At, B1); PG8_BAR; PG8_SCHED;
;     ...
;     PG8_WAIT_V(0);
;     if constexpr (!ALIGN_EPI) { if (wr == 0) PG8_BAR; }
;     PG8_BAR;
;     __builtin_amdgcn_s_setprio(0);
	s_add_i32 s48, s72, s58
	v_lshl_add_u64 v[200:201], v[200:201], 0, s[14:15]
	s_mov_b32 m0, s48
	ds_read_b128 v[176:179], v162 offset:49152
	ds_read_b128 v[180:183], v162 offset:50176
	ds_read_b128 v[184:187], v162 offset:51200
	ds_read_b128 v[188:191], v162 offset:52224
	ds_read_b128 v[192:195], v162 offset:53248
	ds_read_b128 v[196:199], v162 offset:54272
	ds_read_b128 v[214:217], v162 offset:55296
	ds_read_b128 v[218:221], v162 offset:56320
	global_load_lds_dwordx4 v[200:201], off
	s_add_i32 m0, s48, 0x2000
	s_add_u32 s46, s46, 0x80080
	v_lshl_add_u64 v[200:201], v[222:223], 0, s[14:15]
	s_addc_u32 s47, s47, 0
	s_add_i32 s48, s73, s58
	global_load_lds_dwordx4 v[200:201], off
	v_lshl_add_u64 v[200:201], s[46:47], 0, v[202:203]
	s_mov_b32 m0, s48
	s_nop 0
	global_load_lds_dwordx4 v[200:201], off
	v_lshl_add_u64 v[200:201], s[46:47], 0, v[150:151]
	s_add_i32 m0, s48, 0x2000
	s_nop 0
	global_load_lds_dwordx4 v[200:201], off
	v_lshl_add_u64 v[200:201], v[224:225], 0, s[14:15]
	s_mov_b32 m0, s56
	s_nop 0
	global_load_lds_dwordx4 v[200:201], off
	v_lshl_add_u64 v[200:201], v[226:227], 0, s[14:15]
	s_mov_b32 m0, s62
	s_nop 0
	global_load_lds_dwordx4 v[200:201], off
	s_waitcnt vmcnt(8)
	s_waitcnt lgkmcnt(0)
	s_barrier
	s_waitcnt lgkmcnt(0)
	v_mfma_f32_16x16x32_bf16 v[62:65], v[130:133], v[176:179], v[62:65]
	v_mfma_f32_16x16x32_bf16 v[58:61], v[138:141], v[176:179], v[58:61]
	v_mfma_f32_16x16x32_bf16 v[46:49], v[130:133], v[184:187], v[46:49]
	v_mfma_f32_16x16x32_bf16 v[42:45], v[138:141], v[184:187], v[42:45]
	v_mfma_f32_16x16x32_bf16 v[30:33], v[130:133], v[192:195], v[30:33]
	v_mfma_f32_16x16x32_bf16 v[26:29], v[138:141], v[192:195], v[26:29]
	v_mfma_f32_16x16x32_bf16 v[14:17], v[130:133], v[214:217], v[14:17]
	v_mfma_f32_16x16x32_bf16 v[10:13], v[138:141], v[214:217], v[10:13]
	v_mfma_f32_16x16x32_bf16 v[62:65], v[134:137], v[180:183], v[62:65]
	v_mfma_f32_16x16x32_bf16 v[58:61], v[142:145], v[180:183], v[58:61]
	v_mfma_f32_16x16x32_bf16 v[46:49], v[134:137], v[188:191], v[46:49]
	v_mfma_f32_16x16x32_bf16 v[42:45], v[142:145], v[188:191], v[42:45]
	v_mfma_f32_16x16x32_bf16 v[30:33], v[134:137], v[196:199], v[30:33]
	v_mfma_f32_16x16x32_bf16 v[26:29], v[142:145], v[196:199], v[26:29]
	v_mfma_f32_16x16x32_bf16 v[14:17], v[134:137], v[218:221], v[14:17]
	v_mfma_f32_16x16x32_bf16 v[10:13], v[142:145], v[218:221], v[10:13]
	v_mfma_f32_16x16x32_bf16 v[54:57], v[156:159], v[176:179], v[54:57]
	v_mfma_f32_16x16x32_bf16 v[50:53], v[168:171], v[176:179], v[50:53]
	v_mfma_f32_16x16x32_bf16 v[38:41], v[156:159], v[184:187], v[38:41]
	v_mfma_f32_16x16x32_bf16 v[34:37], v[168:171], v[184:187], v[34:37]
	v_mfma_f32_16x16x32_bf16 v[22:25], v[156:159], v[192:195], v[22:25]
	v_mfma_f32_16x16x32_bf16 v[18:21], v[168:171], v[192:195], v[18:21]
	v_mfma_f32_16x16x32_bf16 v[6:9], v[156:159], v[214:217], v[6:9]
	v_mfma_f32_16x16x32_bf16 v[2:5], v[168:171], v[214:217], v[2:5]
	v_mfma_f32_16x16x32_bf16 v[54:57], v[164:167], v[180:183], v[54:57]
	v_mfma_f32_16x16x32_bf16 v[50:53], v[172:175], v[180:183], v[50:53]
	v_mfma_f32_16x16x32_bf16 v[38:41], v[164:167], v[188:191], v[38:41]
	v_mfma_f32_16x16x32_bf16 v[34:37], v[172:175], v[188:191], v[34:37]
	v_mfma_f32_16x16x32_bf16 v[22:25], v[164:167], v[196:199], v[22:25]
	v_mfma_f32_16x16x32_bf16 v[18:21], v[172:175], v[196:199], v[18:21]
	v_mfma_f32_16x16x32_bf16 v[6:9], v[164:167], v[218:221], v[6:9]
	v_mfma_f32_16x16x32_bf16 v[2:5], v[172:175], v[218:221], v[2:5]
	s_barrier
	s_add_i32 s71, s71, 2
	s_add_u32 s69, s69, 0x100
	s_addc_u32 s70, s70, 0
	s_add_u32 s42, s42, 0x100
	s_addc_u32 s43, s43, 0
	s_cmp_gt_u32 s71, 29
	s_cbranch_scc0 .LBB0_1490
	v_lshl_or_b32 v156, s64, 8, v161
	v_ashrrev_i32_e32 v157, 31, v156
	s_branch .LBB0_1486
.LBB0_1499:
	v_mov_b32_e32 v228, 0x358637bd
	v_mov_b32_e32 v229, 0x260
	v_mov_b32_e32 v230, 0x3727c5ac
	v_mov_b32_e32 v231, 0x7ff
	v_mov_b32_e32 v232, 0xff
	v_mov_b32_e32 v233, 0x800
	v_mov_b32_e32 v234, 0x100
	v_mov_b32_e32 v235, 0x7f800000
	v_mov_b32_e32 v236, 0x7fc00000
	v_mov_b32_e32 v237, 0xff800000
	v_mov_b32_e32 v238, 0x600
	v_mov_b32_e32 v239, 0x42800000
	v_not_b32_e32 v240, 63
	v_mov_b32_e32 v241, 0x60000
	v_mov_b64_e32 v[242:243], 0x47
	s_waitcnt vmcnt(0)
	s_cmpk_gt_u32 s5, 0xff
	s_cbranch_scc1 .LBB0_1501
	s_barrier
